# weight conversion: second 32-row half of each tile (data + row scale) is loaded with the first half and its separate load/wait round is skipped (matrices without a mu factor, full 64x64 tiles)
# speedup vs baseline: 1.0069x; 1.0069x over previous
_Z4mega4Args:
	s_load_dwordx2 s[34:35], s[0:1], 0x100
	s_mov_b32 s101, 0
	v_and_b32_e32 v202, 0x3ff, v0
	v_writelane_b32 v251, s2, 0
	v_cmp_gt_u32_e32 vcc, 2, v202
	s_and_saveexec_b64 s[2:3], vcc
	v_lshl_add_u32 v1, v202, 2, 0
	v_add_u32_e32 v1, 0x23fc0, v1
	v_mov_b32_e32 v2, 0
	ds_write_b32 v1, v2
	s_or_b64 exec, exec, s[2:3]
	s_load_dwordx16 s[12:27], s[0:1], 0xc0
	s_waitcnt lgkmcnt(0)
	s_barrier
	s_load_dwordx2 s[28:29], s[0:1], 0x108
	s_add_u32 s4, s0, 0x108
	s_addc_u32 s5, s1, 0
	s_cmp_gt_i32 s35, -1
	s_cbranch_scc1 .LBB0_14
	v_lshrrev_b32_e32 v1, 20, v0
	v_lshrrev_b32_e32 v0, 10, v0
	v_or_b32_e32 v0, v0, v1
	s_movk_i32 s2, 0x3ff
	v_and_or_b32 v0, v0, s2, v202
	v_cmp_eq_u32_e32 vcc, 0, v0
	s_waitcnt lgkmcnt(0)
	s_barrier
	s_and_saveexec_b64 s[2:3], vcc
	s_cbranch_execz .LBB0_13
	buffer_wbl2 sc1
	s_load_dwordx2 s[4:5], s[4:5], 0x58
	s_mov_b64 s[6:7], exec
	v_mbcnt_lo_u32_b32 v0, s6, 0
	v_mbcnt_hi_u32_b32 v0, s7, v0
	v_cmp_eq_u32_e32 vcc, 0, v0
	s_waitcnt lgkmcnt(0)
	s_load_dword s10, s[4:5], 0x28
	s_and_saveexec_b64 s[8:9], vcc
	s_cbranch_execz .LBB0_6
	s_bcnt1_i32_b64 s6, s[6:7]
	v_mov_b32_e32 v1, 0
	v_mov_b32_e32 v2, s6
	global_atomic_add v1, v1, v2, s[4:5] offset:32 sc0

.LBB0_211:
	s_add_i32 s34, s70, 63
	s_lshr_b32 s79, s34, 6
	s_add_i32 s34, s37, 63
	s_ashr_i32 s66, s34, 6
	s_mul_i32 s34, s11, 37
	s_add_i32 s34, s10, s34
	s_ashr_i32 s67, s34, 31
	s_abs_i32 s34, s34
	v_readlane_b32 s35, v251, 63
	s_mul_hi_u32 s35, s34, s35
	v_readlane_b32 s40, v251, 62
	s_mul_i32 s35, s35, s40
	s_sub_i32 s34, s34, s35
	s_sub_i32 s35, s34, s40
	s_cmp_ge_u32 s34, s40
	s_cselect_b32 s34, s35, s34
	s_sub_i32 s35, s34, s40
	s_cmp_ge_u32 s34, s40
	s_cselect_b32 s34, s35, s34
	s_xor_b32 s68, s34, s67
	s_sub_i32 s82, s68, s67
	s_mul_i32 s79, s79, s66
	s_cmp_lg_u64 s[6:7], 0
	s_cselect_b64 s[34:35], -1, 0
	s_cmp_lt_i32 s82, s79
	s_cselect_b64 s[40:41], -1, 0
	s_and_b64 vcc, exec, s[40:41]
	s_cbranch_vccz .LBB0_233
	s_abs_i32 s42, s66
	v_cvt_f32_u32_e32 v0, s42
	s_sub_i32 s45, 0, s42
	s_abs_i32 s44, s82
	s_xor_b32 s43, s82, s66
	v_rcp_iflag_f32_e32 v0, v0
	s_ashr_i32 s43, s43, 31
	v_mov_b32_e32 v2, v202
	v_mul_f32_e32 v0, 0x4f7ffffe, v0
	v_cvt_u32_f32_e32 v0, v0
	s_waitcnt lgkmcnt(0)
	v_ashrrev_i32_e32 v3, 4, v2
	v_mov_b32_e32 v46, 1.0
	v_readfirstlane_b32 s64, v0
	s_mul_i32 s45, s45, s64
	s_mul_hi_u32 s45, s64, s45
	s_add_i32 s64, s64, s45
	s_mul_hi_u32 s45, s44, s64
	s_mul_i32 s64, s45, s42
	s_sub_i32 s44, s44, s64
	s_add_i32 s65, s45, 1
	s_sub_i32 s64, s44, s42
	s_cmp_ge_u32 s44, s42
	s_cselect_b32 s45, s65, s45
	s_cselect_b32 s44, s64, s44
	s_add_i32 s64, s45, 1
	s_cmp_ge_u32 s44, s42
	s_cselect_b32 s42, s64, s45
	s_xor_b32 s42, s42, s43
	s_sub_i32 s43, s42, s43
	s_mul_i32 s42, s43, s66
	s_sub_i32 s42, s82, s42
	v_lshlrev_b32_e32 v0, 2, v2
	v_lshl_add_u32 v56, s43, 6, v3
	v_mov_b32_e32 v2, v1
	v_mov_b32_e32 v3, v1
	s_lshl_b32 s42, s42, 6
	v_and_b32_e32 v41, 60, v0
	v_mov_b32_e32 v0, v1
	v_mov_b64_e32 v[22:23], v[2:3]
	v_or_b32_e32 v43, s42, v41
	s_ashr_i32 s43, s42, 31
	v_cmp_gt_i32_e32 vcc, s70, v56
	v_mov_b64_e32 v[20:21], v[0:1]
	s_and_saveexec_b64 s[44:45], vcc
	s_cbranch_execz .LBB0_222
	v_mov_b32_e32 v2, v1
	v_mov_b32_e32 v3, v1
	v_mov_b32_e32 v0, v1
	v_mov_b64_e32 v[22:23], v[2:3]
	v_cmp_gt_i32_e32 vcc, s37, v43
	v_mov_b64_e32 v[20:21], v[0:1]
	s_and_saveexec_b64 s[64:65], vcc
	s_cbranch_execz .LBB0_215
	v_mad_i64_i32 v[2:3], s[84:85], v56, s37, 0
	v_lshl_add_u64 v[2:3], v[2:3], 2, s[0:1]
	v_lshl_add_u64 v[2:3], s[42:43], 2, v[2:3]
	v_lshlrev_b32_e32 v0, 2, v41
	v_lshl_add_u64 v[2:3], v[2:3], 0, v[0:1]
	global_load_dwordx4 v[20:23], v[2:3], off
	s_cmp_lt_i32 s70, 64
	s_cbranch_scc1 .Lc2_skip0
	s_and_b32 s100, s37, 63
	s_cmp_lg_u32 s100, 0
	s_cbranch_scc1 .Lc2_skip0
	s_lshl_b32 s100, s37, 7
	v_add_co_u32_e32 v70, vcc, s100, v2
	s_nop 1
	v_addc_co_u32_e32 v71, vcc, 0, v3, vcc
	s_cmp_lg_u32 s39, 0
	s_cbranch_scc1 .Lc2_pf0
	s_mov_b32 s101, 1
	global_load_dwordx4 v[36:39], v[70:71], off
	s_cmp_lg_u64 s[34:35], 0
	s_cbranch_scc0 .Lc2_skip0
	v_add_u32_e32 v66, 32, v56
	v_mov_b32_e32 v67, 0
	v_lshl_add_u64 v[68:69], v[66:67], 2, s[6:7]
	global_load_dword v67, v[68:69], off
	s_branch .Lc2_skip0
.Lc2_pf0:
	global_load_dwordx4 v[66:69], v[70:71], off

.LBB0_222:
	s_or_b64 exec, exec, s[44:45]
	s_waitcnt vmcnt(0)
	s_cmp_eq_u32 s101, 1
	s_mov_b32 s101, 0
	s_cbranch_scc0 .Lc2_slow0
	v_mov_b32_e32 v54, 1.0
	v_cndmask_b32_e64 v54, v54, v67, s[34:35]
	s_branch .Lc2_end0
.Lc2_slow0:
	v_add_u32_e32 v0, 32, v56
	v_cmp_gt_i32_e32 vcc, s70, v0
	v_mov_b32_e32 v54, 1.0
	v_mov_b32_e32 v39, 0
	v_mov_b32_e32 v38, 0
	v_mov_b32_e32 v37, 0
	v_mov_b32_e32 v36, 0
	s_and_saveexec_b64 s[44:45], vcc
	s_cbranch_execz .LBB0_232
	v_cmp_gt_i32_e32 vcc, s37, v43
	v_mov_b32_e32 v36, 0
	v_mov_b32_e32 v37, 0
	v_mov_b32_e32 v38, 0
	v_mov_b32_e32 v39, 0
	s_and_saveexec_b64 s[64:65], vcc
	s_cbranch_execz .LBB0_225
	v_mad_i64_i32 v[2:3], s[84:85], v0, s37, 0
	v_lshl_add_u64 v[2:3], v[2:3], 2, s[0:1]
	v_lshl_add_u64 v[2:3], s[42:43], 2, v[2:3]
	v_lshlrev_b32_e32 v0, 2, v41
	v_lshl_add_u64 v[2:3], v[2:3], 0, v[0:1]
	global_load_dwordx4 v[36:39], v[2:3], off

.Lc2_end0:
.LBB0_233:
	v_readlane_b32 s42, v251, 60
	s_add_i32 s69, s82, s42
	s_cmp_ge_i32 s69, s79
	s_cbranch_scc1 .LBB0_255
	s_abs_i32 s42, s66
	s_waitcnt vmcnt(0)
	v_cvt_f32_u32_e32 v0, s42
	s_sub_i32 s45, 0, s42
	s_abs_i32 s44, s69
	s_xor_b32 s43, s69, s66
	v_rcp_iflag_f32_e32 v0, v0
	s_ashr_i32 s43, s43, 31
	v_mov_b32_e32 v2, v202
	v_mul_f32_e32 v0, 0x4f7ffffe, v0
	v_cvt_u32_f32_e32 v0, v0
	s_waitcnt lgkmcnt(0)
	v_ashrrev_i32_e32 v3, 4, v2
	v_mov_b32_e32 v44, 1.0
	v_readfirstlane_b32 s64, v0
	s_mul_i32 s45, s45, s64
	s_mul_hi_u32 s45, s64, s45
	s_add_i32 s64, s64, s45
	s_mul_hi_u32 s45, s44, s64
	s_mul_i32 s64, s45, s42
	s_sub_i32 s44, s44, s64
	s_add_i32 s65, s45, 1
	s_sub_i32 s64, s44, s42
	s_cmp_ge_u32 s44, s42
	s_cselect_b32 s45, s65, s45
	s_cselect_b32 s44, s64, s44
	s_add_i32 s64, s45, 1
	s_cmp_ge_u32 s44, s42
	s_cselect_b32 s42, s64, s45
	s_xor_b32 s42, s42, s43
	s_sub_i32 s43, s42, s43
	s_mul_i32 s42, s43, s66
	s_sub_i32 s42, s69, s42
	v_lshlrev_b32_e32 v0, 2, v2
	v_lshl_add_u32 v56, s43, 6, v3
	v_mov_b32_e32 v2, v1
	v_mov_b32_e32 v3, v1
	s_lshl_b32 s42, s42, 6
	v_and_b32_e32 v41, 60, v0
	v_mov_b32_e32 v0, v1
	v_mov_b64_e32 v[18:19], v[2:3]
	v_or_b32_e32 v43, s42, v41
	s_ashr_i32 s43, s42, 31
	v_cmp_gt_i32_e32 vcc, s70, v56
	v_mov_b64_e32 v[16:17], v[0:1]
	s_and_saveexec_b64 s[44:45], vcc
	s_cbranch_execz .LBB0_244
	v_mov_b32_e32 v2, v1
	v_mov_b32_e32 v3, v1
	v_mov_b32_e32 v0, v1
	v_mov_b64_e32 v[18:19], v[2:3]
	v_cmp_gt_i32_e32 vcc, s37, v43
	v_mov_b64_e32 v[16:17], v[0:1]
	s_and_saveexec_b64 s[64:65], vcc
	s_cbranch_execz .LBB0_237
	v_mad_i64_i32 v[2:3], s[84:85], v56, s37, 0
	v_lshl_add_u64 v[2:3], v[2:3], 2, s[0:1]
	v_lshl_add_u64 v[2:3], s[42:43], 2, v[2:3]
	v_lshlrev_b32_e32 v0, 2, v41
	v_lshl_add_u64 v[2:3], v[2:3], 0, v[0:1]
	global_load_dwordx4 v[16:19], v[2:3], off
	s_cmp_lt_i32 s70, 64
	s_cbranch_scc1 .Lc2_skip1
	s_and_b32 s100, s37, 63
	s_cmp_lg_u32 s100, 0
	s_cbranch_scc1 .Lc2_skip1
	s_lshl_b32 s100, s37, 7
	v_add_co_u32_e32 v70, vcc, s100, v2
	s_nop 1
	v_addc_co_u32_e32 v71, vcc, 0, v3, vcc
	s_cmp_lg_u32 s39, 0
	s_cbranch_scc1 .Lc2_pf1
	s_mov_b32 s101, 1
	global_load_dwordx4 v[32:35], v[70:71], off
	s_cmp_lg_u64 s[34:35], 0
	s_cbranch_scc0 .Lc2_skip1
	v_add_u32_e32 v66, 32, v56
	v_mov_b32_e32 v67, 0
	v_lshl_add_u64 v[68:69], v[66:67], 2, s[6:7]
	global_load_dword v67, v[68:69], off
	s_branch .Lc2_skip1

.LBB0_244:
	s_or_b64 exec, exec, s[44:45]
	s_waitcnt vmcnt(0)
	s_cmp_eq_u32 s101, 1
	s_mov_b32 s101, 0
	s_cbranch_scc0 .Lc2_slow1
	v_mov_b32_e32 v50, 1.0
	v_cndmask_b32_e64 v50, v50, v67, s[34:35]
	s_branch .Lc2_end1
.Lc2_slow1:
	v_add_u32_e32 v0, 32, v56
	v_cmp_gt_i32_e32 vcc, s70, v0
	v_mov_b32_e32 v50, 1.0
	v_mov_b32_e32 v35, 0
	v_mov_b32_e32 v34, 0
	v_mov_b32_e32 v33, 0
	v_mov_b32_e32 v32, 0
	s_and_saveexec_b64 s[44:45], vcc
	s_cbranch_execz .LBB0_254
	v_cmp_gt_i32_e32 vcc, s37, v43
	v_mov_b32_e32 v32, 0
	v_mov_b32_e32 v33, 0
	v_mov_b32_e32 v34, 0
	v_mov_b32_e32 v35, 0
	s_and_saveexec_b64 s[64:65], vcc
	s_cbranch_execz .LBB0_247
	v_mad_i64_i32 v[2:3], s[84:85], v0, s37, 0
	v_lshl_add_u64 v[2:3], v[2:3], 2, s[0:1]
	v_lshl_add_u64 v[2:3], s[42:43], 2, v[2:3]
	v_lshlrev_b32_e32 v0, 2, v41
	v_lshl_add_u64 v[2:3], v[2:3], 0, v[0:1]
	global_load_dwordx4 v[32:35], v[2:3], off

.Lc2_end1:
.LBB0_255:
	v_readlane_b32 s42, v251, 60
	s_add_i32 s69, s69, s42
	s_cmp_ge_i32 s69, s79
	s_cbranch_scc1 .LBB0_277
	s_abs_i32 s42, s66
	s_waitcnt vmcnt(0)
	v_cvt_f32_u32_e32 v0, s42
	s_sub_i32 s45, 0, s42
	s_abs_i32 s44, s69
	s_xor_b32 s43, s69, s66
	v_rcp_iflag_f32_e32 v0, v0
	s_ashr_i32 s43, s43, 31
	v_mov_b32_e32 v2, v202
	v_mul_f32_e32 v0, 0x4f7ffffe, v0
	v_cvt_u32_f32_e32 v0, v0
	s_waitcnt lgkmcnt(0)
	v_ashrrev_i32_e32 v3, 4, v2
	v_mov_b32_e32 v40, 1.0
	v_readfirstlane_b32 s64, v0
	s_mul_i32 s45, s45, s64
	s_mul_hi_u32 s45, s64, s45
	s_add_i32 s64, s64, s45
	s_mul_hi_u32 s45, s44, s64
	s_mul_i32 s64, s45, s42
	s_sub_i32 s44, s44, s64
	s_add_i32 s65, s45, 1
	s_sub_i32 s64, s44, s42
	s_cmp_ge_u32 s44, s42
	s_cselect_b32 s45, s65, s45
	s_cselect_b32 s44, s64, s44
	s_add_i32 s64, s45, 1
	s_cmp_ge_u32 s44, s42
	s_cselect_b32 s42, s64, s45
	s_xor_b32 s42, s42, s43
	s_sub_i32 s43, s42, s43
	s_mul_i32 s42, s43, s66
	s_sub_i32 s42, s69, s42
	v_lshlrev_b32_e32 v0, 2, v2
	v_lshl_add_u32 v56, s43, 6, v3
	v_mov_b32_e32 v2, v1
	v_mov_b32_e32 v3, v1
	s_lshl_b32 s42, s42, 6
	v_and_b32_e32 v41, 60, v0
	v_mov_b32_e32 v0, v1
	v_mov_b64_e32 v[14:15], v[2:3]
	v_or_b32_e32 v43, s42, v41
	s_ashr_i32 s43, s42, 31
	v_cmp_gt_i32_e32 vcc, s70, v56
	v_mov_b64_e32 v[12:13], v[0:1]
	s_and_saveexec_b64 s[44:45], vcc
	s_cbranch_execz .LBB0_266
	v_mov_b32_e32 v2, v1
	v_mov_b32_e32 v3, v1
	v_mov_b32_e32 v0, v1
	v_mov_b64_e32 v[14:15], v[2:3]
	v_cmp_gt_i32_e32 vcc, s37, v43
	v_mov_b64_e32 v[12:13], v[0:1]
	s_and_saveexec_b64 s[64:65], vcc
	s_cbranch_execz .LBB0_259
	v_mad_i64_i32 v[2:3], s[84:85], v56, s37, 0
	v_lshl_add_u64 v[2:3], v[2:3], 2, s[0:1]
	v_lshl_add_u64 v[2:3], s[42:43], 2, v[2:3]
	v_lshlrev_b32_e32 v0, 2, v41
	v_lshl_add_u64 v[2:3], v[2:3], 0, v[0:1]
	global_load_dwordx4 v[12:15], v[2:3], off
	s_cmp_lt_i32 s70, 64
	s_cbranch_scc1 .Lc2_skip2
	s_and_b32 s100, s37, 63
	s_cmp_lg_u32 s100, 0
	s_cbranch_scc1 .Lc2_skip2
	s_lshl_b32 s100, s37, 7
	v_add_co_u32_e32 v70, vcc, s100, v2
	s_nop 1
	v_addc_co_u32_e32 v71, vcc, 0, v3, vcc
	s_cmp_lg_u32 s39, 0
	s_cbranch_scc1 .Lc2_pf2
	s_mov_b32 s101, 1
	global_load_dwordx4 v[28:31], v[70:71], off
	s_cmp_lg_u64 s[34:35], 0
	s_cbranch_scc0 .Lc2_skip2
	v_add_u32_e32 v66, 32, v56
	v_mov_b32_e32 v67, 0
	v_lshl_add_u64 v[68:69], v[66:67], 2, s[6:7]
	global_load_dword v67, v[68:69], off
	s_branch .Lc2_skip2

.LBB0_266:
	s_or_b64 exec, exec, s[44:45]
	s_waitcnt vmcnt(0)
	s_cmp_eq_u32 s101, 1
	s_mov_b32 s101, 0
	s_cbranch_scc0 .Lc2_slow2
	v_mov_b32_e32 v48, 1.0
	v_cndmask_b32_e64 v48, v48, v67, s[34:35]
	s_branch .Lc2_end2
.Lc2_slow2:
	v_add_u32_e32 v0, 32, v56
	v_cmp_gt_i32_e32 vcc, s70, v0
	v_mov_b32_e32 v48, 1.0
	v_mov_b32_e32 v31, 0
	v_mov_b32_e32 v30, 0
	v_mov_b32_e32 v29, 0
	v_mov_b32_e32 v28, 0
	s_and_saveexec_b64 s[44:45], vcc
	s_cbranch_execz .LBB0_276
	v_cmp_gt_i32_e32 vcc, s37, v43
	v_mov_b32_e32 v28, 0
	v_mov_b32_e32 v29, 0
	v_mov_b32_e32 v30, 0
	v_mov_b32_e32 v31, 0
	s_and_saveexec_b64 s[64:65], vcc
	s_cbranch_execz .LBB0_269
	v_mad_i64_i32 v[2:3], s[84:85], v0, s37, 0
	v_lshl_add_u64 v[2:3], v[2:3], 2, s[0:1]
	v_lshl_add_u64 v[2:3], s[42:43], 2, v[2:3]
	v_lshlrev_b32_e32 v0, 2, v41
	v_lshl_add_u64 v[2:3], v[2:3], 0, v[0:1]
	global_load_dwordx4 v[28:31], v[2:3], off

.Lc2_end2:
.LBB0_277:
	v_readlane_b32 s42, v251, 60
	s_add_i32 s69, s69, s42
	s_cmp_ge_i32 s69, s79
	s_cbranch_scc1 .LBB0_299
	s_abs_i32 s42, s66
	s_waitcnt vmcnt(0)
	v_cvt_f32_u32_e32 v0, s42
	s_sub_i32 s45, 0, s42
	s_abs_i32 s44, s69
	s_xor_b32 s43, s69, s66
	v_rcp_iflag_f32_e32 v0, v0
	s_ashr_i32 s43, s43, 31
	v_mov_b32_e32 v2, v202
	v_mul_f32_e32 v0, 0x4f7ffffe, v0
	v_cvt_u32_f32_e32 v0, v0
	s_waitcnt lgkmcnt(0)
	v_ashrrev_i32_e32 v3, 4, v2
	v_mov_b32_e32 v42, 1.0
	v_readfirstlane_b32 s64, v0
	s_mul_i32 s45, s45, s64
	s_mul_hi_u32 s45, s64, s45
	s_add_i32 s64, s64, s45
	s_mul_hi_u32 s45, s44, s64
	s_mul_i32 s64, s45, s42
	s_sub_i32 s44, s44, s64
	s_add_i32 s65, s45, 1
	s_sub_i32 s64, s44, s42
	s_cmp_ge_u32 s44, s42
	s_cselect_b32 s45, s65, s45
	s_cselect_b32 s44, s64, s44
	s_add_i32 s64, s45, 1
	s_cmp_ge_u32 s44, s42
	s_cselect_b32 s42, s64, s45
	s_xor_b32 s42, s42, s43
	s_sub_i32 s43, s42, s43
	s_mul_i32 s42, s43, s66
	s_sub_i32 s42, s69, s42
	v_lshlrev_b32_e32 v0, 2, v2
	v_lshl_add_u32 v56, s43, 6, v3
	v_mov_b32_e32 v2, v1
	v_mov_b32_e32 v3, v1
	s_lshl_b32 s42, s42, 6
	v_and_b32_e32 v41, 60, v0
	v_mov_b32_e32 v0, v1
	v_mov_b64_e32 v[10:11], v[2:3]
	v_or_b32_e32 v43, s42, v41
	s_ashr_i32 s43, s42, 31
	v_cmp_gt_i32_e32 vcc, s70, v56
	v_mov_b64_e32 v[8:9], v[0:1]
	s_and_saveexec_b64 s[44:45], vcc
	s_cbranch_execz .LBB0_288
	v_mov_b32_e32 v2, v1
	v_mov_b32_e32 v3, v1
	v_mov_b32_e32 v0, v1
	v_mov_b64_e32 v[10:11], v[2:3]
	v_cmp_gt_i32_e32 vcc, s37, v43
	v_mov_b64_e32 v[8:9], v[0:1]
	s_and_saveexec_b64 s[64:65], vcc
	s_cbranch_execz .LBB0_281
	v_mad_i64_i32 v[2:3], s[84:85], v56, s37, 0
	v_lshl_add_u64 v[2:3], v[2:3], 2, s[0:1]
	v_lshl_add_u64 v[2:3], s[42:43], 2, v[2:3]
	v_lshlrev_b32_e32 v0, 2, v41
	v_lshl_add_u64 v[2:3], v[2:3], 0, v[0:1]
	global_load_dwordx4 v[8:11], v[2:3], off
	s_cmp_lt_i32 s70, 64
	s_cbranch_scc1 .Lc2_skip3
	s_and_b32 s100, s37, 63
	s_cmp_lg_u32 s100, 0
	s_cbranch_scc1 .Lc2_skip3
	s_lshl_b32 s100, s37, 7
	v_add_co_u32_e32 v70, vcc, s100, v2
	s_nop 1
	v_addc_co_u32_e32 v71, vcc, 0, v3, vcc
	s_cmp_lg_u32 s39, 0
	s_cbranch_scc1 .Lc2_pf3
	s_mov_b32 s101, 1
	global_load_dwordx4 v[24:27], v[70:71], off
	s_cmp_lg_u64 s[34:35], 0
	s_cbranch_scc0 .Lc2_skip3
	v_add_u32_e32 v66, 32, v56
	v_mov_b32_e32 v67, 0
	v_lshl_add_u64 v[68:69], v[66:67], 2, s[6:7]
	global_load_dword v67, v[68:69], off
	s_branch .Lc2_skip3

.LBB0_288:
	s_or_b64 exec, exec, s[44:45]
	s_waitcnt vmcnt(0)
	s_cmp_eq_u32 s101, 1
	s_mov_b32 s101, 0
	s_cbranch_scc0 .Lc2_slow3
	v_mov_b32_e32 v52, 1.0
	v_cndmask_b32_e64 v52, v52, v67, s[34:35]
	s_branch .Lc2_end3
.Lc2_slow3:
	v_add_u32_e32 v0, 32, v56
	v_cmp_gt_i32_e32 vcc, s70, v0
	v_mov_b32_e32 v52, 1.0
	v_mov_b32_e32 v27, 0
	v_mov_b32_e32 v26, 0
	v_mov_b32_e32 v25, 0
	v_mov_b32_e32 v24, 0
	s_and_saveexec_b64 s[44:45], vcc
	s_cbranch_execz .LBB0_298
	v_cmp_gt_i32_e32 vcc, s37, v43
	v_mov_b32_e32 v24, 0
	v_mov_b32_e32 v25, 0
	v_mov_b32_e32 v26, 0
	v_mov_b32_e32 v27, 0
	s_and_saveexec_b64 s[64:65], vcc
	s_cbranch_execz .LBB0_291
	v_mad_i64_i32 v[2:3], s[84:85], v0, s37, 0
	v_lshl_add_u64 v[2:3], v[2:3], 2, s[0:1]
	v_lshl_add_u64 v[2:3], s[42:43], 2, v[2:3]
	v_lshlrev_b32_e32 v0, 2, v41
	v_lshl_add_u64 v[2:3], v[2:3], 0, v[0:1]
	global_load_dwordx4 v[24:27], v[2:3], off

.Lc2_end3:
.LBB0_299:
	s_and_b64 vcc, exec, s[40:41]
	s_cbranch_vccz .LBB0_159
	s_abs_i32 s83, s66
	s_waitcnt vmcnt(0)
	v_cvt_f32_u32_e32 v0, s83
	s_lshl_b32 s40, s68, 6
	s_lshl_b32 s41, s67, 6
	s_sub_i32 s42, 0, s83
	v_rcp_iflag_f32_e32 v0, v0
	s_sub_i32 s86, s40, s41
	s_lshl_b32 s85, s66, 6
	s_ashr_i32 s84, s66, 31
	v_mul_f32_e32 v0, 0x4f7ffffe, v0
	v_cvt_u32_f32_e32 v0, v0
	s_sub_i32 s88, 0, s85
	v_readfirstlane_b32 s40, v0
	s_mul_i32 s42, s42, s40
	s_mul_hi_u32 s41, s40, s42
	s_add_i32 s87, s40, s41

.LBB0_314:
	s_or_b64 exec, exec, s[40:41]
	v_readlane_b32 s40, v251, 55
	s_add_i32 s89, s82, s40
	s_waitcnt lgkmcnt(0)
	s_barrier
	s_cmp_ge_i32 s89, s79
	s_cselect_b64 s[40:41], -1, 0
	s_and_b64 vcc, exec, s[40:41]
	s_cbranch_vccnz .LBB0_342
	s_abs_i32 s43, s89
	s_mul_hi_u32 s44, s43, s87
	s_mul_i32 s45, s44, s83
	s_ashr_i32 s42, s89, 31
	s_sub_i32 s43, s43, s45
	s_xor_b32 s42, s42, s84
	s_add_i32 s45, s44, 1
	s_sub_i32 s64, s43, s83
	s_cmp_ge_u32 s43, s83
	s_cselect_b32 s44, s45, s44
	s_cselect_b32 s43, s64, s43
	s_add_i32 s45, s44, 1
	s_cmp_ge_u32 s43, s83
	v_mov_b32_e32 v0, v202
	s_cselect_b32 s43, s45, s44
	s_xor_b32 s43, s43, s42
	s_sub_i32 s43, s43, s42
	v_ashrrev_i32_e32 v2, 4, v0
	v_lshlrev_b32_e32 v0, 2, v0
	s_mul_i32 s42, s88, s43
	v_readlane_b32 s44, v252, 10
	v_and_b32_e32 v41, 60, v0
	v_lshl_add_u32 v56, s43, 6, v2
	s_mul_i32 s43, s85, s43
	s_add_i32 s44, s44, s86
	v_subrev_u32_e32 v0, s43, v41
	v_mov_b32_e32 v2, v1
	v_mov_b32_e32 v3, v1
	s_add_i32 s42, s44, s42
	v_add_u32_e32 v43, s44, v0
	v_mov_b32_e32 v0, v1
	v_mov_b64_e32 v[22:23], v[2:3]
	s_ashr_i32 s43, s42, 31
	v_cmp_gt_i32_e32 vcc, s70, v56
	v_mov_b32_e32 v46, 1.0
	v_mov_b64_e32 v[20:21], v[0:1]
	s_and_saveexec_b64 s[44:45], vcc
	s_cbranch_execz .LBB0_328
	v_mov_b32_e32 v2, v1
	v_mov_b32_e32 v3, v1
	v_mov_b32_e32 v0, v1
	v_mov_b64_e32 v[22:23], v[2:3]
	v_cmp_gt_i32_e32 vcc, s37, v43
	v_mov_b64_e32 v[20:21], v[0:1]
	s_and_saveexec_b64 s[64:65], vcc
	s_cbranch_execz .LBB0_318
	v_mad_i64_i32 v[2:3], s[66:67], v56, s37, 0
	v_lshl_add_u64 v[2:3], v[2:3], 2, s[0:1]
	v_lshl_add_u64 v[2:3], s[42:43], 2, v[2:3]
	v_lshlrev_b32_e32 v0, 2, v41
	v_lshl_add_u64 v[2:3], v[2:3], 0, v[0:1]
	global_load_dwordx4 v[20:23], v[2:3], off
	s_cmp_lt_i32 s70, 64
	s_cbranch_scc1 .Lc2_skip4
	s_and_b32 s100, s37, 63
	s_cmp_lg_u32 s100, 0
	s_cbranch_scc1 .Lc2_skip4
	s_lshl_b32 s100, s37, 7
	v_add_co_u32_e32 v70, vcc, s100, v2
	s_nop 1
	v_addc_co_u32_e32 v71, vcc, 0, v3, vcc
	s_cmp_lg_u32 s39, 0
	s_cbranch_scc1 .Lc2_pf4
	s_mov_b32 s101, 1
	global_load_dwordx4 v[36:39], v[70:71], off
	s_cmp_lg_u64 s[34:35], 0
	s_cbranch_scc0 .Lc2_skip4
	v_add_u32_e32 v66, 32, v56
	v_mov_b32_e32 v67, 0
	v_lshl_add_u64 v[68:69], v[66:67], 2, s[6:7]
	global_load_dword v67, v[68:69], off
	s_branch .Lc2_skip4

.Lc2_slow4:
	v_add_u32_e32 v0, 32, v56
	v_cmp_gt_i32_e32 vcc, s70, v0
	v_mov_b32_e32 v54, 1.0
	v_mov_b32_e32 v39, 0
	v_mov_b32_e32 v38, 0
	v_mov_b32_e32 v37, 0
	v_mov_b32_e32 v36, 0
	s_and_saveexec_b64 s[44:45], vcc
	s_cbranch_execz .LBB0_341
	v_cmp_gt_i32_e32 vcc, s37, v43
	v_mov_b32_e32 v36, 0
	v_mov_b32_e32 v37, 0
	v_mov_b32_e32 v38, 0
	v_mov_b32_e32 v39, 0
	s_and_saveexec_b64 s[64:65], vcc
	s_cbranch_execz .LBB0_331
	v_mad_i64_i32 v[2:3], s[66:67], v0, s37, 0
	v_lshl_add_u64 v[2:3], v[2:3], 2, s[0:1]
	v_lshl_add_u64 v[2:3], s[42:43], 2, v[2:3]
	v_lshlrev_b32_e32 v0, 2, v41
	v_lshl_add_u64 v[2:3], v[2:3], 0, v[0:1]
	global_load_dwordx4 v[36:39], v[2:3], off

.Lc2_end4:
.LBB0_342:
	v_readlane_b32 s42, v251, 60
	s_add_i32 s42, s42, s82
	s_cmp_ge_i32 s42, s79
	s_cbranch_scc1 .LBB0_384
	s_ashr_i32 s43, s42, 31
	s_abs_i32 s42, s42
	s_mul_hi_u32 s44, s42, s87
	s_mul_i32 s45, s44, s83
	s_sub_i32 s42, s42, s45
	s_xor_b32 s43, s43, s84
	s_add_i32 s45, s44, 1
	s_sub_i32 s64, s42, s83
	s_waitcnt vmcnt(0)
	v_mov_b32_e32 v0, v202
	s_cmp_ge_u32 s42, s83
	s_cselect_b32 s44, s45, s44
	v_ashrrev_i32_e32 v2, 4, v0
	v_lshlrev_b32_e32 v3, 4, v0
	s_cselect_b32 s42, s64, s42
	s_add_i32 s45, s44, 1
	v_and_b32_e32 v3, 0xf0, v3
	v_mul_lo_u32 v2, v2, s3
	s_cmp_ge_u32 s42, s83
	v_add3_u32 v41, 0, v3, v2
	v_pk_mul_f32 v[2:3], v[44:45], v[16:17] op_sel_hi:[0,1]
	s_cselect_b32 s42, s45, s44
	ds_write2_b32 v41, v2, v3 offset1:1
	v_pk_mul_f32 v[2:3], v[44:45], v[18:19] op_sel_hi:[0,1]
	s_xor_b32 s42, s42, s43
	ds_write2_b32 v41, v2, v3 offset0:2 offset1:3
	v_add_u32_e32 v43, 0x2080, v41
	v_pk_mul_f32 v[2:3], v[50:51], v[32:33] op_sel_hi:[0,1]
	s_sub_i32 s44, s42, s43
	ds_write2_b32 v43, v2, v3 offset1:1
	v_add_u32_e32 v41, 0x2088, v41
	v_pk_mul_f32 v[2:3], v[50:51], v[34:35] op_sel_hi:[0,1]
	ds_write2_b32 v41, v2, v3 offset1:1
	v_ashrrev_i32_e32 v2, 3, v0
	s_mul_i32 s42, s85, s44
	v_subrev_u32_e32 v3, s42, v2
	v_readlane_b32 s42, v252, 16
	s_waitcnt lgkmcnt(0)
	s_barrier
	s_add_i32 s42, s42, s86
	v_add_u32_e32 v41, s42, v3
	v_cmp_gt_i32_e32 vcc, s37, v41
	s_and_saveexec_b64 s[42:43], vcc
	s_cbranch_execz .LBB0_356
	v_lshlrev_b32_e32 v0, 3, v0
	s_lshl_b32 s44, s44, 6
	v_and_b32_e32 v0, 56, v0
	v_or_b32_e32 v3, s44, v0
	v_cmp_gt_i32_e32 vcc, s71, v3
	s_and_b64 exec, exec, vcc
	s_cbranch_execz .LBB0_356
	v_lshlrev_b32_e32 v45, 2, v2
	v_mul_u32_u24_e32 v2, 0x104, v0
	v_add3_u32 v43, 0, v45, v2
	ds_read2_b32 v[2:3], v43 offset1:65
	ds_read2_b32 v[56:57], v43 offset0:130 offset1:195
	v_add_u32_e32 v43, 0x400, v43
	ds_read2_b32 v[58:59], v43 offset0:4 offset1:69
	ds_read2_b32 v[60:61], v43 offset0:134 offset1:199
	s_mov_b64 s[68:69], -1
	s_mov_b64 s[64:65], 0
	s_cmp_lt_i32 s38, 2
	s_mov_b64 s[66:67], 0
	s_cbranch_scc1 .LBB0_351
	s_cmp_eq_u32 s38, 2
	s_mov_b64 s[66:67], -1
	s_cbranch_scc0 .LBB0_348
	v_and_b32_e32 v43, 0x80, v45
	v_lshrrev_b32_e32 v45, 1, v41
	v_and_b32_e32 v45, 0x60, v45
	v_and_b32_e32 v47, 0xffffff1f, v41
	v_or3_b32 v43, v47, v43, v45
	s_mov_b64 s[66:67], 0

.LBB0_356:
	s_or_b64 exec, exec, s[42:43]
	s_waitcnt lgkmcnt(0)
	s_barrier
	v_readlane_b32 s42, v252, 17
	s_add_i32 s42, s42, s82
	s_cmp_ge_i32 s42, s79
	s_cbranch_scc1 .LBB0_384
	s_ashr_i32 s43, s42, 31
	s_abs_i32 s42, s42
	s_mul_hi_u32 s44, s42, s87
	s_mul_i32 s45, s44, s83
	s_sub_i32 s42, s42, s45
	s_xor_b32 s43, s43, s84
	s_add_i32 s45, s44, 1
	s_sub_i32 s64, s42, s83
	s_cmp_ge_u32 s42, s83
	s_cselect_b32 s44, s45, s44
	s_cselect_b32 s42, s64, s42
	s_add_i32 s45, s44, 1
	s_cmp_ge_u32 s42, s83
	v_mov_b32_e32 v0, v202
	s_cselect_b32 s42, s45, s44
	s_xor_b32 s42, s42, s43
	s_sub_i32 s43, s42, s43
	v_ashrrev_i32_e32 v2, 4, v0
	v_lshlrev_b32_e32 v0, 2, v0
	s_mul_i32 s42, s88, s43
	v_readlane_b32 s44, v252, 18
	v_and_b32_e32 v41, 60, v0
	v_lshl_add_u32 v56, s43, 6, v2
	s_mul_i32 s43, s85, s43
	s_add_i32 s44, s44, s86
	v_subrev_u32_e32 v0, s43, v41
	v_mov_b32_e32 v2, v1
	v_mov_b32_e32 v3, v1
	s_add_i32 s42, s44, s42
	v_add_u32_e32 v43, s44, v0
	v_mov_b32_e32 v0, v1
	v_mov_b64_e32 v[18:19], v[2:3]
	s_ashr_i32 s43, s42, 31
	v_cmp_gt_i32_e32 vcc, s70, v56
	v_mov_b32_e32 v44, 1.0
	v_mov_b64_e32 v[16:17], v[0:1]
	s_and_saveexec_b64 s[44:45], vcc
	s_cbranch_execz .LBB0_370
	v_mov_b32_e32 v2, v1
	v_mov_b32_e32 v3, v1
	v_mov_b32_e32 v0, v1
	v_mov_b64_e32 v[18:19], v[2:3]
	v_cmp_gt_i32_e32 vcc, s37, v43
	v_mov_b64_e32 v[16:17], v[0:1]
	s_and_saveexec_b64 s[64:65], vcc
	s_cbranch_execz .LBB0_360
	v_mad_i64_i32 v[2:3], s[66:67], v56, s37, 0
	v_lshl_add_u64 v[2:3], v[2:3], 2, s[0:1]
	v_lshl_add_u64 v[2:3], s[42:43], 2, v[2:3]
	v_lshlrev_b32_e32 v0, 2, v41
	v_lshl_add_u64 v[2:3], v[2:3], 0, v[0:1]
	global_load_dwordx4 v[16:19], v[2:3], off
	s_cmp_lt_i32 s70, 64
	s_cbranch_scc1 .Lc2_skip5
	s_and_b32 s100, s37, 63
	s_cmp_lg_u32 s100, 0
	s_cbranch_scc1 .Lc2_skip5
	s_lshl_b32 s100, s37, 7
	v_add_co_u32_e32 v70, vcc, s100, v2
	s_nop 1
	v_addc_co_u32_e32 v71, vcc, 0, v3, vcc
	s_cmp_lg_u32 s39, 0
	s_cbranch_scc1 .Lc2_pf5
	s_mov_b32 s101, 1
	global_load_dwordx4 v[32:35], v[70:71], off
	s_cmp_lg_u64 s[34:35], 0
	s_cbranch_scc0 .Lc2_skip5
	v_add_u32_e32 v66, 32, v56
	v_mov_b32_e32 v67, 0
	v_lshl_add_u64 v[68:69], v[66:67], 2, s[6:7]
	global_load_dword v67, v[68:69], off
	s_branch .Lc2_skip5

.Lc2_slow5:
	v_add_u32_e32 v0, 32, v56
	v_cmp_gt_i32_e32 vcc, s70, v0
	v_mov_b32_e32 v50, 1.0
	v_mov_b32_e32 v35, 0
	v_mov_b32_e32 v34, 0
	v_mov_b32_e32 v33, 0
	v_mov_b32_e32 v32, 0
	s_and_saveexec_b64 s[44:45], vcc
	s_cbranch_execz .LBB0_383
	v_cmp_gt_i32_e32 vcc, s37, v43
	v_mov_b32_e32 v32, 0
	v_mov_b32_e32 v33, 0
	v_mov_b32_e32 v34, 0
	v_mov_b32_e32 v35, 0
	s_and_saveexec_b64 s[64:65], vcc
	s_cbranch_execz .LBB0_373
	v_mad_i64_i32 v[2:3], s[66:67], v0, s37, 0
	v_lshl_add_u64 v[2:3], v[2:3], 2, s[0:1]
	v_lshl_add_u64 v[2:3], s[42:43], 2, v[2:3]
	v_lshlrev_b32_e32 v0, 2, v41
	v_lshl_add_u64 v[2:3], v[2:3], 0, v[0:1]
	global_load_dwordx4 v[32:35], v[2:3], off

.Lc2_end5:
.LBB0_384:
	v_readlane_b32 s42, v251, 56
	s_add_i32 s42, s42, s82
	s_cmp_ge_i32 s42, s79
	s_cbranch_scc1 .LBB0_426
	s_ashr_i32 s43, s42, 31
	s_abs_i32 s42, s42
	s_mul_hi_u32 s44, s42, s87
	s_mul_i32 s45, s44, s83
	s_sub_i32 s42, s42, s45
	s_waitcnt vmcnt(0)
	v_mov_b32_e32 v0, v202
	s_xor_b32 s43, s43, s84
	s_add_i32 s45, s44, 1
	s_sub_i32 s64, s42, s83
	s_cmp_ge_u32 s42, s83
	v_ashrrev_i32_e32 v2, 4, v0
	v_lshlrev_b32_e32 v3, 4, v0
	s_cselect_b32 s44, s45, s44
	v_and_b32_e32 v3, 0xf0, v3
	v_mul_lo_u32 v2, v2, s3
	s_cselect_b32 s42, s64, s42
	s_add_i32 s45, s44, 1
	v_add3_u32 v41, 0, v3, v2
	s_cmp_ge_u32 s42, s83
	v_pk_mul_f32 v[2:3], v[40:41], v[12:13] op_sel_hi:[0,1]
	s_cselect_b32 s42, s45, s44
	ds_write2_b32 v41, v2, v3 offset1:1
	v_pk_mul_f32 v[2:3], v[40:41], v[14:15] op_sel_hi:[0,1]
	s_xor_b32 s42, s42, s43
	ds_write2_b32 v41, v2, v3 offset0:2 offset1:3
	v_add_u32_e32 v43, 0x2080, v41
	v_pk_mul_f32 v[2:3], v[48:49], v[28:29] op_sel_hi:[0,1]
	s_sub_i32 s44, s42, s43
	ds_write2_b32 v43, v2, v3 offset1:1
	v_add_u32_e32 v41, 0x2088, v41
	v_pk_mul_f32 v[2:3], v[48:49], v[30:31] op_sel_hi:[0,1]
	ds_write2_b32 v41, v2, v3 offset1:1
	v_ashrrev_i32_e32 v2, 3, v0
	s_mul_i32 s42, s85, s44
	v_subrev_u32_e32 v3, s42, v2
	v_readlane_b32 s42, v252, 13
	s_waitcnt lgkmcnt(0)
	s_barrier
	s_add_i32 s42, s42, s86
	v_add_u32_e32 v41, s42, v3
	v_cmp_gt_i32_e32 vcc, s37, v41
	s_and_saveexec_b64 s[42:43], vcc
	s_cbranch_execz .LBB0_398
	v_lshlrev_b32_e32 v0, 3, v0
	s_lshl_b32 s44, s44, 6
	v_and_b32_e32 v0, 56, v0
	v_or_b32_e32 v3, s44, v0
	v_cmp_gt_i32_e32 vcc, s71, v3
	s_and_b64 exec, exec, vcc
	s_cbranch_execz .LBB0_398
	v_lshlrev_b32_e32 v45, 2, v2
	v_mul_u32_u24_e32 v2, 0x104, v0
	v_add3_u32 v43, 0, v45, v2
	ds_read2_b32 v[2:3], v43 offset1:65
	ds_read2_b32 v[56:57], v43 offset0:130 offset1:195
	v_add_u32_e32 v43, 0x400, v43
	ds_read2_b32 v[58:59], v43 offset0:4 offset1:69
	ds_read2_b32 v[60:61], v43 offset0:134 offset1:199
	s_mov_b64 s[68:69], -1
	s_mov_b64 s[64:65], 0
	s_cmp_lt_i32 s38, 2
	s_mov_b64 s[66:67], 0
	s_cbranch_scc1 .LBB0_393
	s_cmp_eq_u32 s38, 2
	s_mov_b64 s[66:67], -1
	s_cbranch_scc0 .LBB0_390
	v_and_b32_e32 v43, 0x80, v45
	v_lshrrev_b32_e32 v45, 1, v41
	v_and_b32_e32 v45, 0x60, v45
	v_and_b32_e32 v47, 0xffffff1f, v41
	v_or3_b32 v43, v47, v43, v45
	s_mov_b64 s[66:67], 0

.LBB0_398:
	s_or_b64 exec, exec, s[42:43]
	s_waitcnt lgkmcnt(0)
	s_barrier
	v_readlane_b32 s42, v252, 14
	s_add_i32 s42, s42, s82
	s_cmp_ge_i32 s42, s79
	s_cbranch_scc1 .LBB0_426
	s_ashr_i32 s43, s42, 31
	s_abs_i32 s42, s42
	s_mul_hi_u32 s44, s42, s87
	s_mul_i32 s45, s44, s83
	s_sub_i32 s42, s42, s45
	s_xor_b32 s43, s43, s84
	s_add_i32 s45, s44, 1
	s_sub_i32 s64, s42, s83
	s_cmp_ge_u32 s42, s83
	s_cselect_b32 s44, s45, s44
	s_cselect_b32 s42, s64, s42
	s_add_i32 s45, s44, 1
	s_cmp_ge_u32 s42, s83
	v_mov_b32_e32 v0, v202
	s_cselect_b32 s42, s45, s44
	s_xor_b32 s42, s42, s43
	s_sub_i32 s43, s42, s43
	v_ashrrev_i32_e32 v2, 4, v0
	v_lshlrev_b32_e32 v0, 2, v0
	s_mul_i32 s42, s88, s43
	v_readlane_b32 s44, v252, 15
	v_and_b32_e32 v41, 60, v0
	v_lshl_add_u32 v56, s43, 6, v2
	s_mul_i32 s43, s85, s43
	s_add_i32 s44, s44, s86
	v_subrev_u32_e32 v0, s43, v41
	v_mov_b32_e32 v2, v1
	v_mov_b32_e32 v3, v1
	s_add_i32 s42, s44, s42
	v_add_u32_e32 v43, s44, v0
	v_mov_b32_e32 v0, v1
	v_mov_b64_e32 v[14:15], v[2:3]
	s_ashr_i32 s43, s42, 31
	v_cmp_gt_i32_e32 vcc, s70, v56
	v_mov_b32_e32 v40, 1.0
	v_mov_b64_e32 v[12:13], v[0:1]
	s_and_saveexec_b64 s[44:45], vcc
	s_cbranch_execz .LBB0_412
	v_mov_b32_e32 v2, v1
	v_mov_b32_e32 v3, v1
	v_mov_b32_e32 v0, v1
	v_mov_b64_e32 v[14:15], v[2:3]
	v_cmp_gt_i32_e32 vcc, s37, v43
	v_mov_b64_e32 v[12:13], v[0:1]
	s_and_saveexec_b64 s[64:65], vcc
	s_cbranch_execz .LBB0_402
	v_mad_i64_i32 v[2:3], s[66:67], v56, s37, 0
	v_lshl_add_u64 v[2:3], v[2:3], 2, s[0:1]
	v_lshl_add_u64 v[2:3], s[42:43], 2, v[2:3]
	v_lshlrev_b32_e32 v0, 2, v41
	v_lshl_add_u64 v[2:3], v[2:3], 0, v[0:1]
	global_load_dwordx4 v[12:15], v[2:3], off
	s_cmp_lt_i32 s70, 64
	s_cbranch_scc1 .Lc2_skip6
	s_and_b32 s100, s37, 63
	s_cmp_lg_u32 s100, 0
	s_cbranch_scc1 .Lc2_skip6
	s_lshl_b32 s100, s37, 7
	v_add_co_u32_e32 v70, vcc, s100, v2
	s_nop 1
	v_addc_co_u32_e32 v71, vcc, 0, v3, vcc
	s_cmp_lg_u32 s39, 0
	s_cbranch_scc1 .Lc2_pf6
	s_mov_b32 s101, 1
	global_load_dwordx4 v[28:31], v[70:71], off
	s_cmp_lg_u64 s[34:35], 0
	s_cbranch_scc0 .Lc2_skip6
	v_add_u32_e32 v66, 32, v56
	v_mov_b32_e32 v67, 0
	v_lshl_add_u64 v[68:69], v[66:67], 2, s[6:7]
	global_load_dword v67, v[68:69], off
	s_branch .Lc2_skip6

.Lc2_slow6:
	v_add_u32_e32 v0, 32, v56
	v_cmp_gt_i32_e32 vcc, s70, v0
	v_mov_b32_e32 v48, 1.0
	v_mov_b32_e32 v31, 0
	v_mov_b32_e32 v30, 0
	v_mov_b32_e32 v29, 0
	v_mov_b32_e32 v28, 0
	s_and_saveexec_b64 s[44:45], vcc
	s_cbranch_execz .LBB0_425
	v_cmp_gt_i32_e32 vcc, s37, v43
	v_mov_b32_e32 v28, 0
	v_mov_b32_e32 v29, 0
	v_mov_b32_e32 v30, 0
	v_mov_b32_e32 v31, 0
	s_and_saveexec_b64 s[64:65], vcc
	s_cbranch_execz .LBB0_415
	v_mad_i64_i32 v[2:3], s[66:67], v0, s37, 0
	v_lshl_add_u64 v[2:3], v[2:3], 2, s[0:1]
	v_lshl_add_u64 v[2:3], s[42:43], 2, v[2:3]
	v_lshlrev_b32_e32 v0, 2, v41
	v_lshl_add_u64 v[2:3], v[2:3], 0, v[0:1]
	global_load_dwordx4 v[28:31], v[2:3], off

.Lc2_end6:
.LBB0_426:
	v_readlane_b32 s42, v251, 57
	s_add_i32 s42, s42, s82
	s_cmp_ge_i32 s42, s79
	s_cbranch_scc1 .LBB0_468
	s_ashr_i32 s43, s42, 31
	s_abs_i32 s42, s42
	s_mul_hi_u32 s44, s42, s87
	s_mul_i32 s45, s44, s83
	s_sub_i32 s42, s42, s45
	s_xor_b32 s43, s43, s84
	s_add_i32 s45, s44, 1
	s_sub_i32 s64, s42, s83
	s_waitcnt vmcnt(0)
	v_mov_b32_e32 v0, v202
	s_cmp_ge_u32 s42, s83
	s_cselect_b32 s44, s45, s44
	v_ashrrev_i32_e32 v2, 4, v0
	v_lshlrev_b32_e32 v3, 4, v0
	s_cselect_b32 s42, s64, s42
	s_add_i32 s45, s44, 1
	v_and_b32_e32 v3, 0xf0, v3
	v_mul_lo_u32 v2, v2, s3
	s_cmp_ge_u32 s42, s83
	v_add3_u32 v41, 0, v3, v2
	v_pk_mul_f32 v[2:3], v[8:9], v[42:43] op_sel_hi:[1,0]
	s_cselect_b32 s42, s45, s44
	ds_write2_b32 v41, v2, v3 offset1:1
	v_pk_mul_f32 v[2:3], v[10:11], v[42:43] op_sel_hi:[1,0]
	s_xor_b32 s42, s42, s43
	ds_write2_b32 v41, v2, v3 offset0:2 offset1:3
	v_add_u32_e32 v43, 0x2080, v41
	v_pk_mul_f32 v[2:3], v[24:25], v[52:53] op_sel_hi:[1,0]
	s_sub_i32 s44, s42, s43
	ds_write2_b32 v43, v2, v3 offset1:1
	v_add_u32_e32 v41, 0x2088, v41
	v_pk_mul_f32 v[2:3], v[26:27], v[52:53] op_sel_hi:[1,0]
	ds_write2_b32 v41, v2, v3 offset1:1
	v_ashrrev_i32_e32 v2, 3, v0
	s_mul_i32 s42, s85, s44
	v_subrev_u32_e32 v3, s42, v2
	v_readlane_b32 s42, v252, 9
	s_waitcnt lgkmcnt(0)
	s_barrier
	s_add_i32 s42, s42, s86
	v_add_u32_e32 v41, s42, v3
	v_cmp_gt_i32_e32 vcc, s37, v41
	s_and_saveexec_b64 s[42:43], vcc
	s_cbranch_execz .LBB0_440
	v_lshlrev_b32_e32 v0, 3, v0
	s_lshl_b32 s44, s44, 6
	v_and_b32_e32 v0, 56, v0
	v_or_b32_e32 v3, s44, v0
	v_cmp_gt_i32_e32 vcc, s71, v3
	s_and_b64 exec, exec, vcc
	s_cbranch_execz .LBB0_440
	v_lshlrev_b32_e32 v45, 2, v2
	v_mul_u32_u24_e32 v2, 0x104, v0
	v_add3_u32 v43, 0, v45, v2
	ds_read2_b32 v[2:3], v43 offset1:65
	ds_read2_b32 v[56:57], v43 offset0:130 offset1:195
	v_add_u32_e32 v43, 0x400, v43
	ds_read2_b32 v[58:59], v43 offset0:4 offset1:69
	ds_read2_b32 v[60:61], v43 offset0:134 offset1:199
	s_mov_b64 s[68:69], -1
	s_mov_b64 s[64:65], 0
	s_cmp_lt_i32 s38, 2
	s_mov_b64 s[66:67], 0
	s_cbranch_scc1 .LBB0_435
	s_cmp_eq_u32 s38, 2
	s_mov_b64 s[66:67], -1
	s_cbranch_scc0 .LBB0_432
	v_and_b32_e32 v43, 0x80, v45
	v_lshrrev_b32_e32 v45, 1, v41
	v_and_b32_e32 v45, 0x60, v45
	v_and_b32_e32 v47, 0xffffff1f, v41
	v_or3_b32 v43, v47, v43, v45
	s_mov_b64 s[66:67], 0

.LBB0_440:
	s_or_b64 exec, exec, s[42:43]
	s_waitcnt lgkmcnt(0)
	s_barrier
	v_readlane_b32 s42, v252, 11
	s_add_i32 s42, s42, s82
	s_cmp_ge_i32 s42, s79
	s_cbranch_scc1 .LBB0_468
	s_ashr_i32 s43, s42, 31
	s_abs_i32 s42, s42
	s_mul_hi_u32 s44, s42, s87
	s_mul_i32 s45, s44, s83
	s_sub_i32 s42, s42, s45
	s_xor_b32 s43, s43, s84
	s_add_i32 s45, s44, 1
	s_sub_i32 s64, s42, s83
	s_cmp_ge_u32 s42, s83
	s_cselect_b32 s44, s45, s44
	s_cselect_b32 s42, s64, s42
	s_add_i32 s45, s44, 1
	s_cmp_ge_u32 s42, s83
	v_mov_b32_e32 v0, v202
	s_cselect_b32 s42, s45, s44
	s_xor_b32 s42, s42, s43
	s_sub_i32 s43, s42, s43
	v_ashrrev_i32_e32 v2, 4, v0
	v_lshlrev_b32_e32 v0, 2, v0
	s_mul_i32 s42, s88, s43
	v_readlane_b32 s44, v252, 12
	v_and_b32_e32 v41, 60, v0
	v_lshl_add_u32 v56, s43, 6, v2
	s_mul_i32 s43, s85, s43
	s_add_i32 s44, s44, s86
	v_subrev_u32_e32 v0, s43, v41
	v_mov_b32_e32 v2, v1
	v_mov_b32_e32 v3, v1
	s_add_i32 s42, s44, s42
	v_add_u32_e32 v43, s44, v0
	v_mov_b32_e32 v0, v1
	v_mov_b64_e32 v[10:11], v[2:3]
	s_ashr_i32 s43, s42, 31
	v_cmp_gt_i32_e32 vcc, s70, v56
	v_mov_b32_e32 v42, 1.0
	v_mov_b64_e32 v[8:9], v[0:1]
	s_and_saveexec_b64 s[44:45], vcc
	s_cbranch_execz .LBB0_454
	v_mov_b32_e32 v2, v1
	v_mov_b32_e32 v3, v1
	v_mov_b32_e32 v0, v1
	v_mov_b64_e32 v[10:11], v[2:3]
	v_cmp_gt_i32_e32 vcc, s37, v43
	v_mov_b64_e32 v[8:9], v[0:1]
	s_and_saveexec_b64 s[64:65], vcc
	s_cbranch_execz .LBB0_444
	v_mad_i64_i32 v[2:3], s[66:67], v56, s37, 0
	v_lshl_add_u64 v[2:3], v[2:3], 2, s[0:1]
	v_lshl_add_u64 v[2:3], s[42:43], 2, v[2:3]
	v_lshlrev_b32_e32 v0, 2, v41
	v_lshl_add_u64 v[2:3], v[2:3], 0, v[0:1]
	global_load_dwordx4 v[8:11], v[2:3], off
	s_cmp_lt_i32 s70, 64
	s_cbranch_scc1 .Lc2_skip7
	s_and_b32 s100, s37, 63
	s_cmp_lg_u32 s100, 0
	s_cbranch_scc1 .Lc2_skip7
	s_lshl_b32 s100, s37, 7
	v_add_co_u32_e32 v70, vcc, s100, v2
	s_nop 1
	v_addc_co_u32_e32 v71, vcc, 0, v3, vcc
	s_cmp_lg_u32 s39, 0
	s_cbranch_scc1 .Lc2_pf7
	s_mov_b32 s101, 1
	global_load_dwordx4 v[24:27], v[70:71], off
	s_cmp_lg_u64 s[34:35], 0
	s_cbranch_scc0 .Lc2_skip7
	v_add_u32_e32 v66, 32, v56
	v_mov_b32_e32 v67, 0
	v_lshl_add_u64 v[68:69], v[66:67], 2, s[6:7]
	global_load_dword v67, v[68:69], off
	s_branch .Lc2_skip7

.Lc2_slow7:
	v_add_u32_e32 v0, 32, v56
	v_cmp_gt_i32_e32 vcc, s70, v0
	v_mov_b32_e32 v52, 1.0
	v_mov_b32_e32 v27, 0
	v_mov_b32_e32 v26, 0
	v_mov_b32_e32 v25, 0
	v_mov_b32_e32 v24, 0
	s_and_saveexec_b64 s[44:45], vcc
	s_cbranch_execz .LBB0_467
	v_cmp_gt_i32_e32 vcc, s37, v43
	v_mov_b32_e32 v24, 0
	v_mov_b32_e32 v25, 0
	v_mov_b32_e32 v26, 0
	v_mov_b32_e32 v27, 0
	s_and_saveexec_b64 s[64:65], vcc
	s_cbranch_execz .LBB0_457
	v_mad_i64_i32 v[2:3], s[66:67], v0, s37, 0
	v_lshl_add_u64 v[2:3], v[2:3], 2, s[0:1]
	v_lshl_add_u64 v[2:3], s[42:43], 2, v[2:3]
	v_lshlrev_b32_e32 v0, 2, v41
	v_lshl_add_u64 v[2:3], v[2:3], 0, v[0:1]
	global_load_dwordx4 v[24:27], v[2:3], off

.Lc2_end7:
.LBB0_468:
	s_andn2_b64 vcc, exec, s[40:41]
	v_readlane_b32 s40, v252, 10
	s_add_i32 s86, s86, s40
	s_cbranch_vccz .LBB0_159
	s_mov_b32 s82, s89
	s_branch .LBB0_301

.LBB0_918:
	s_add_i32 s0, s64, 63
	s_lshr_b32 s67, s0, 6
	s_add_i32 s0, s70, 63
	s_ashr_i32 s42, s0, 6
	s_mul_i32 s0, s69, 37
	s_add_i32 s0, s0, s68
	s_ashr_i32 s43, s0, 31
	s_abs_i32 s0, s0
	v_readlane_b32 s1, v252, 1
	s_mul_hi_u32 s1, s0, s1
	v_readlane_b32 s4, v252, 0
	s_mul_i32 s1, s1, s4
	s_sub_i32 s0, s0, s1
	s_sub_i32 s1, s0, s4
	s_cmp_ge_u32 s0, s4
	s_cselect_b32 s0, s1, s0
	s_sub_i32 s1, s0, s4
	s_cmp_ge_u32 s0, s4
	s_cselect_b32 s0, s1, s0
	s_xor_b32 s44, s0, s43
	s_sub_i32 s76, s44, s43
	s_mul_i32 s67, s67, s42
	s_cmp_lg_u64 s[30:31], 0
	s_cselect_b64 s[0:1], -1, 0
	s_cmp_lt_i32 s76, s67
	s_cselect_b64 s[4:5], -1, 0
	s_and_b64 vcc, exec, s[4:5]
	s_cbranch_vccz .LBB0_963
	s_abs_i32 s36, s42
	v_cvt_f32_u32_e32 v0, s36
	s_sub_i32 s39, 0, s36
	s_abs_i32 s38, s76
	s_xor_b32 s37, s76, s42
	v_rcp_iflag_f32_e32 v0, v0
	s_ashr_i32 s37, s37, 31
	v_mov_b32_e32 v2, v202
	v_mul_f32_e32 v0, 0x4f7ffffe, v0
	v_cvt_u32_f32_e32 v0, v0
	v_ashrrev_i32_e32 v3, 4, v2
	v_mov_b32_e32 v46, 1.0
	v_readfirstlane_b32 s40, v0
	s_mul_i32 s39, s39, s40
	s_mul_hi_u32 s39, s40, s39
	s_add_i32 s40, s40, s39
	s_mul_hi_u32 s39, s38, s40
	s_mul_i32 s40, s39, s36
	s_sub_i32 s38, s38, s40
	s_add_i32 s41, s39, 1
	s_sub_i32 s40, s38, s36
	s_cmp_ge_u32 s38, s36
	s_cselect_b32 s39, s41, s39
	s_cselect_b32 s38, s40, s38
	s_add_i32 s40, s39, 1
	s_cmp_ge_u32 s38, s36
	s_cselect_b32 s36, s40, s39
	s_xor_b32 s36, s36, s37
	s_sub_i32 s37, s36, s37
	s_mul_i32 s36, s37, s42
	s_sub_i32 s36, s76, s36
	v_lshlrev_b32_e32 v0, 2, v2
	v_lshl_add_u32 v56, s37, 6, v3
	v_mov_b32_e32 v2, v1
	v_mov_b32_e32 v3, v1
	s_lshl_b32 s36, s36, 6
	v_and_b32_e32 v41, 60, v0
	v_mov_b32_e32 v0, v1
	v_mov_b64_e32 v[22:23], v[2:3]
	v_or_b32_e32 v43, s36, v41
	s_ashr_i32 s37, s36, 31
	v_cmp_gt_i32_e32 vcc, s64, v56
	v_mov_b64_e32 v[20:21], v[0:1]
	s_and_saveexec_b64 s[38:39], vcc
	s_cbranch_execz .LBB0_929
	v_mov_b32_e32 v2, v1
	v_mov_b32_e32 v3, v1
	v_mov_b32_e32 v0, v1
	v_mov_b64_e32 v[22:23], v[2:3]
	v_cmp_gt_i32_e32 vcc, s70, v43
	v_mov_b64_e32 v[20:21], v[0:1]
	s_and_saveexec_b64 s[40:41], vcc
	s_cbranch_execz .LBB0_922
	v_mad_i64_i32 v[2:3], s[78:79], v56, s70, 0
	v_lshl_add_u64 v[2:3], v[2:3], 2, s[10:11]
	v_lshl_add_u64 v[2:3], s[36:37], 2, v[2:3]
	v_lshlrev_b32_e32 v0, 2, v41
	v_lshl_add_u64 v[2:3], v[2:3], 0, v[0:1]
	global_load_dwordx4 v[20:23], v[2:3], off
	s_cmp_lt_i32 s64, 64
	s_cbranch_scc1 .Lc2_skip8
	s_and_b32 s100, s70, 63
	s_cmp_lg_u32 s100, 0
	s_cbranch_scc1 .Lc2_skip8
	s_lshl_b32 s100, s70, 7
	v_add_co_u32_e32 v70, vcc, s100, v2
	s_nop 1
	v_addc_co_u32_e32 v71, vcc, 0, v3, vcc
	s_cmp_lg_u32 s72, 0
	s_cbranch_scc1 .Lc2_pf8
	s_mov_b32 s101, 1
	global_load_dwordx4 v[36:39], v[70:71], off
	s_cmp_lg_u64 s[0:1], 0
	s_cbranch_scc0 .Lc2_skip8
	v_add_u32_e32 v66, 32, v56
	v_mov_b32_e32 v67, 0
	v_lshl_add_u64 v[68:69], v[66:67], 2, s[30:31]
	global_load_dword v67, v[68:69], off
	s_branch .Lc2_skip8

.LBB0_929:
	s_or_b64 exec, exec, s[38:39]
	s_waitcnt vmcnt(0)
	s_cmp_eq_u32 s101, 1
	s_mov_b32 s101, 0
	s_cbranch_scc0 .Lc2_slow8
	v_mov_b32_e32 v52, 1.0
	v_cndmask_b32_e64 v52, v52, v67, s[0:1]
	s_branch .Lc2_end8
.Lc2_slow8:
	v_add_u32_e32 v0, 32, v56
	v_cmp_gt_i32_e32 vcc, s64, v0
	v_mov_b32_e32 v52, 1.0
	v_mov_b32_e32 v39, 0
	v_mov_b32_e32 v38, 0
	v_mov_b32_e32 v37, 0
	v_mov_b32_e32 v36, 0
	s_and_saveexec_b64 s[38:39], vcc
	s_cbranch_execz .LBB0_939
	v_cmp_gt_i32_e32 vcc, s70, v43
	v_mov_b32_e32 v36, 0
	v_mov_b32_e32 v37, 0
	v_mov_b32_e32 v38, 0
	v_mov_b32_e32 v39, 0
	s_and_saveexec_b64 s[40:41], vcc
	s_cbranch_execz .LBB0_932
	v_mad_i64_i32 v[2:3], s[78:79], v0, s70, 0
	v_lshl_add_u64 v[2:3], v[2:3], 2, s[10:11]
	v_lshl_add_u64 v[2:3], s[36:37], 2, v[2:3]
	v_lshlrev_b32_e32 v0, 2, v41
	v_lshl_add_u64 v[2:3], v[2:3], 0, v[0:1]
	global_load_dwordx4 v[36:39], v[2:3], off

.Lc2_end8:
	s_add_i32 s45, s76, s28
	s_cmp_ge_i32 s45, s67
	s_cbranch_scc0 .LBB0_964

.LBB0_941:
	s_abs_i32 s36, s42
	s_waitcnt vmcnt(0)
	v_cvt_f32_u32_e32 v0, s36
	s_sub_i32 s39, 0, s36
	s_abs_i32 s38, s45
	s_xor_b32 s37, s45, s42
	v_rcp_iflag_f32_e32 v0, v0
	s_ashr_i32 s37, s37, 31
	v_mov_b32_e32 v2, v202
	v_mul_f32_e32 v0, 0x4f7ffffe, v0
	v_cvt_u32_f32_e32 v0, v0
	v_ashrrev_i32_e32 v3, 4, v2
	v_mov_b32_e32 v40, 1.0
	v_readfirstlane_b32 s40, v0
	s_mul_i32 s39, s39, s40
	s_mul_hi_u32 s39, s40, s39
	s_add_i32 s40, s40, s39
	s_mul_hi_u32 s39, s38, s40
	s_mul_i32 s40, s39, s36
	s_sub_i32 s38, s38, s40
	s_add_i32 s41, s39, 1
	s_sub_i32 s40, s38, s36
	s_cmp_ge_u32 s38, s36
	s_cselect_b32 s39, s41, s39
	s_cselect_b32 s38, s40, s38
	s_add_i32 s40, s39, 1
	s_cmp_ge_u32 s38, s36
	s_cselect_b32 s36, s40, s39
	s_xor_b32 s36, s36, s37
	s_sub_i32 s37, s36, s37
	s_mul_i32 s36, s37, s42
	s_sub_i32 s36, s45, s36
	v_lshlrev_b32_e32 v0, 2, v2
	v_lshl_add_u32 v56, s37, 6, v3
	v_mov_b32_e32 v2, v1
	v_mov_b32_e32 v3, v1
	s_lshl_b32 s36, s36, 6
	v_and_b32_e32 v41, 60, v0
	v_mov_b32_e32 v0, v1
	v_mov_b64_e32 v[14:15], v[2:3]
	v_or_b32_e32 v43, s36, v41
	s_ashr_i32 s37, s36, 31
	v_cmp_gt_i32_e32 vcc, s64, v56
	v_mov_b64_e32 v[12:13], v[0:1]
	s_and_saveexec_b64 s[38:39], vcc
	s_cbranch_execz .LBB0_951
	v_mov_b32_e32 v2, v1
	v_mov_b32_e32 v3, v1
	v_mov_b32_e32 v0, v1
	v_mov_b64_e32 v[14:15], v[2:3]
	v_cmp_gt_i32_e32 vcc, s70, v43
	v_mov_b64_e32 v[12:13], v[0:1]
	s_and_saveexec_b64 s[40:41], vcc
	s_cbranch_execz .LBB0_944
	v_mad_i64_i32 v[2:3], s[78:79], v56, s70, 0
	v_lshl_add_u64 v[2:3], v[2:3], 2, s[10:11]
	v_lshl_add_u64 v[2:3], s[36:37], 2, v[2:3]
	v_lshlrev_b32_e32 v0, 2, v41
	v_lshl_add_u64 v[2:3], v[2:3], 0, v[0:1]
	global_load_dwordx4 v[12:15], v[2:3], off
	s_cmp_lt_i32 s64, 64
	s_cbranch_scc1 .Lc2_skip9
	s_and_b32 s100, s70, 63
	s_cmp_lg_u32 s100, 0
	s_cbranch_scc1 .Lc2_skip9
	s_lshl_b32 s100, s70, 7
	v_add_co_u32_e32 v70, vcc, s100, v2
	s_nop 1
	v_addc_co_u32_e32 v71, vcc, 0, v3, vcc
	s_cmp_lg_u32 s72, 0
	s_cbranch_scc1 .Lc2_pf9
	s_mov_b32 s101, 1
	global_load_dwordx4 v[28:31], v[70:71], off
	s_cmp_lg_u64 s[0:1], 0
	s_cbranch_scc0 .Lc2_skip9
	v_add_u32_e32 v66, 32, v56
	v_mov_b32_e32 v67, 0
	v_lshl_add_u64 v[68:69], v[66:67], 2, s[30:31]
	global_load_dword v67, v[68:69], off
	s_branch .Lc2_skip9

.LBB0_951:
	s_or_b64 exec, exec, s[38:39]
	s_waitcnt vmcnt(0)
	s_cmp_eq_u32 s101, 1
	s_mov_b32 s101, 0
	s_cbranch_scc0 .Lc2_slow9
	v_mov_b32_e32 v48, 1.0
	v_cndmask_b32_e64 v48, v48, v67, s[0:1]
	s_branch .Lc2_end9
.Lc2_slow9:
	v_add_u32_e32 v0, 32, v56
	v_cmp_gt_i32_e32 vcc, s64, v0
	v_mov_b32_e32 v48, 1.0
	v_mov_b32_e32 v31, 0
	v_mov_b32_e32 v30, 0
	v_mov_b32_e32 v29, 0
	v_mov_b32_e32 v28, 0
	s_and_saveexec_b64 s[38:39], vcc
	s_cbranch_execz .LBB0_961
	v_cmp_gt_i32_e32 vcc, s70, v43
	v_mov_b32_e32 v28, 0
	v_mov_b32_e32 v29, 0
	v_mov_b32_e32 v30, 0
	v_mov_b32_e32 v31, 0
	s_and_saveexec_b64 s[40:41], vcc
	s_cbranch_execz .LBB0_954
	v_mad_i64_i32 v[2:3], s[78:79], v0, s70, 0
	v_lshl_add_u64 v[2:3], v[2:3], 2, s[10:11]
	v_lshl_add_u64 v[2:3], s[36:37], 2, v[2:3]
	v_lshlrev_b32_e32 v0, 2, v41
	v_lshl_add_u64 v[2:3], v[2:3], 0, v[0:1]
	global_load_dwordx4 v[28:31], v[2:3], off

.Lc2_end9:
	s_add_i32 s45, s45, s28
	s_cmp_ge_i32 s45, s67
	s_cbranch_scc0 .LBB0_986

.LBB0_964:
	s_abs_i32 s36, s42
	s_waitcnt vmcnt(0)
	v_cvt_f32_u32_e32 v0, s36
	s_sub_i32 s39, 0, s36
	s_abs_i32 s38, s45
	s_xor_b32 s37, s45, s42
	v_rcp_iflag_f32_e32 v0, v0
	s_ashr_i32 s37, s37, 31
	v_mov_b32_e32 v2, v202
	v_mul_f32_e32 v0, 0x4f7ffffe, v0
	v_cvt_u32_f32_e32 v0, v0
	v_ashrrev_i32_e32 v3, 4, v2
	v_mov_b32_e32 v44, 1.0
	v_readfirstlane_b32 s40, v0
	s_mul_i32 s39, s39, s40
	s_mul_hi_u32 s39, s40, s39
	s_add_i32 s40, s40, s39
	s_mul_hi_u32 s39, s38, s40
	s_mul_i32 s40, s39, s36
	s_sub_i32 s38, s38, s40
	s_add_i32 s41, s39, 1
	s_sub_i32 s40, s38, s36
	s_cmp_ge_u32 s38, s36
	s_cselect_b32 s39, s41, s39
	s_cselect_b32 s38, s40, s38
	s_add_i32 s40, s39, 1
	s_cmp_ge_u32 s38, s36
	s_cselect_b32 s36, s40, s39
	s_xor_b32 s36, s36, s37
	s_sub_i32 s37, s36, s37
	s_mul_i32 s36, s37, s42
	s_sub_i32 s36, s45, s36
	v_lshlrev_b32_e32 v0, 2, v2
	v_lshl_add_u32 v56, s37, 6, v3
	v_mov_b32_e32 v2, v1
	v_mov_b32_e32 v3, v1
	s_lshl_b32 s36, s36, 6
	v_and_b32_e32 v41, 60, v0
	v_mov_b32_e32 v0, v1
	v_mov_b64_e32 v[18:19], v[2:3]
	v_or_b32_e32 v43, s36, v41
	s_ashr_i32 s37, s36, 31
	v_cmp_gt_i32_e32 vcc, s64, v56
	v_mov_b64_e32 v[16:17], v[0:1]
	s_and_saveexec_b64 s[38:39], vcc
	s_cbranch_execz .LBB0_974
	v_mov_b32_e32 v2, v1
	v_mov_b32_e32 v3, v1
	v_mov_b32_e32 v0, v1
	v_mov_b64_e32 v[18:19], v[2:3]
	v_cmp_gt_i32_e32 vcc, s70, v43
	v_mov_b64_e32 v[16:17], v[0:1]
	s_and_saveexec_b64 s[40:41], vcc
	s_cbranch_execz .LBB0_967
	v_mad_i64_i32 v[2:3], s[78:79], v56, s70, 0
	v_lshl_add_u64 v[2:3], v[2:3], 2, s[10:11]
	v_lshl_add_u64 v[2:3], s[36:37], 2, v[2:3]
	v_lshlrev_b32_e32 v0, 2, v41
	v_lshl_add_u64 v[2:3], v[2:3], 0, v[0:1]
	global_load_dwordx4 v[16:19], v[2:3], off
	s_cmp_lt_i32 s64, 64
	s_cbranch_scc1 .Lc2_skip10
	s_and_b32 s100, s70, 63
	s_cmp_lg_u32 s100, 0
	s_cbranch_scc1 .Lc2_skip10
	s_lshl_b32 s100, s70, 7
	v_add_co_u32_e32 v70, vcc, s100, v2
	s_nop 1
	v_addc_co_u32_e32 v71, vcc, 0, v3, vcc
	s_cmp_lg_u32 s72, 0
	s_cbranch_scc1 .Lc2_pf10
	s_mov_b32 s101, 1
	global_load_dwordx4 v[32:35], v[70:71], off
	s_cmp_lg_u64 s[0:1], 0
	s_cbranch_scc0 .Lc2_skip10
	v_add_u32_e32 v66, 32, v56
	v_mov_b32_e32 v67, 0
	v_lshl_add_u64 v[68:69], v[66:67], 2, s[30:31]
	global_load_dword v67, v[68:69], off
	s_branch .Lc2_skip10

.LBB0_974:
	s_or_b64 exec, exec, s[38:39]
	s_waitcnt vmcnt(0)
	s_cmp_eq_u32 s101, 1
	s_mov_b32 s101, 0
	s_cbranch_scc0 .Lc2_slow10
	v_mov_b32_e32 v50, 1.0
	v_cndmask_b32_e64 v50, v50, v67, s[0:1]
	s_branch .Lc2_end10
.Lc2_slow10:
	v_add_u32_e32 v0, 32, v56
	v_cmp_gt_i32_e32 vcc, s64, v0
	v_mov_b32_e32 v50, 1.0
	v_mov_b32_e32 v35, 0
	v_mov_b32_e32 v34, 0
	v_mov_b32_e32 v33, 0
	v_mov_b32_e32 v32, 0
	s_and_saveexec_b64 s[38:39], vcc
	s_cbranch_execz .LBB0_984
	v_cmp_gt_i32_e32 vcc, s70, v43
	v_mov_b32_e32 v32, 0
	v_mov_b32_e32 v33, 0
	v_mov_b32_e32 v34, 0
	v_mov_b32_e32 v35, 0
	s_and_saveexec_b64 s[40:41], vcc
	s_cbranch_execz .LBB0_977
	v_mad_i64_i32 v[2:3], s[78:79], v0, s70, 0
	v_lshl_add_u64 v[2:3], v[2:3], 2, s[10:11]
	v_lshl_add_u64 v[2:3], s[36:37], 2, v[2:3]
	v_lshlrev_b32_e32 v0, 2, v41
	v_lshl_add_u64 v[2:3], v[2:3], 0, v[0:1]
	global_load_dwordx4 v[32:35], v[2:3], off

.LBB0_986:
	s_abs_i32 s36, s42
	s_waitcnt vmcnt(0)
	v_cvt_f32_u32_e32 v0, s36
	s_sub_i32 s39, 0, s36
	s_abs_i32 s38, s45
	s_xor_b32 s37, s45, s42
	v_rcp_iflag_f32_e32 v0, v0
	s_ashr_i32 s37, s37, 31
	v_mov_b32_e32 v2, v202
	v_mul_f32_e32 v0, 0x4f7ffffe, v0
	v_cvt_u32_f32_e32 v0, v0
	v_ashrrev_i32_e32 v3, 4, v2
	v_mov_b32_e32 v42, 1.0
	v_readfirstlane_b32 s40, v0
	s_mul_i32 s39, s39, s40
	s_mul_hi_u32 s39, s40, s39
	s_add_i32 s40, s40, s39
	s_mul_hi_u32 s39, s38, s40
	s_mul_i32 s40, s39, s36
	s_sub_i32 s38, s38, s40
	s_add_i32 s41, s39, 1
	s_sub_i32 s40, s38, s36
	s_cmp_ge_u32 s38, s36
	s_cselect_b32 s39, s41, s39
	s_cselect_b32 s38, s40, s38
	s_add_i32 s40, s39, 1
	s_cmp_ge_u32 s38, s36
	s_cselect_b32 s36, s40, s39
	s_xor_b32 s36, s36, s37
	s_sub_i32 s37, s36, s37
	s_mul_i32 s36, s37, s42
	s_sub_i32 s36, s45, s36
	v_lshlrev_b32_e32 v0, 2, v2
	v_lshl_add_u32 v56, s37, 6, v3
	v_mov_b32_e32 v2, v1
	v_mov_b32_e32 v3, v1
	s_lshl_b32 s36, s36, 6
	v_and_b32_e32 v41, 60, v0
	v_mov_b32_e32 v0, v1
	s_waitcnt lgkmcnt(0)
	v_mov_b64_e32 v[10:11], v[2:3]
	v_or_b32_e32 v43, s36, v41
	s_ashr_i32 s37, s36, 31
	v_cmp_gt_i32_e32 vcc, s64, v56
	v_mov_b64_e32 v[8:9], v[0:1]
	s_and_saveexec_b64 s[38:39], vcc
	s_cbranch_execz .LBB0_996
	v_mov_b32_e32 v2, v1
	v_mov_b32_e32 v3, v1
	v_mov_b32_e32 v0, v1
	v_mov_b64_e32 v[10:11], v[2:3]
	v_cmp_gt_i32_e32 vcc, s70, v43
	v_mov_b64_e32 v[8:9], v[0:1]
	s_and_saveexec_b64 s[40:41], vcc
	s_cbranch_execz .LBB0_989
	v_mad_i64_i32 v[2:3], s[78:79], v56, s70, 0
	v_lshl_add_u64 v[2:3], v[2:3], 2, s[10:11]
	v_lshl_add_u64 v[2:3], s[36:37], 2, v[2:3]
	v_lshlrev_b32_e32 v0, 2, v41
	v_lshl_add_u64 v[2:3], v[2:3], 0, v[0:1]
	global_load_dwordx4 v[8:11], v[2:3], off
	s_cmp_lt_i32 s64, 64
	s_cbranch_scc1 .Lc2_skip11
	s_and_b32 s100, s70, 63
	s_cmp_lg_u32 s100, 0
	s_cbranch_scc1 .Lc2_skip11
	s_lshl_b32 s100, s70, 7
	v_add_co_u32_e32 v70, vcc, s100, v2
	s_nop 1
	v_addc_co_u32_e32 v71, vcc, 0, v3, vcc
	s_cmp_lg_u32 s72, 0
	s_cbranch_scc1 .Lc2_pf11
	s_mov_b32 s101, 1
	global_load_dwordx4 v[24:27], v[70:71], off
	s_cmp_lg_u64 s[0:1], 0
	s_cbranch_scc0 .Lc2_skip11
	v_add_u32_e32 v66, 32, v56
	v_mov_b32_e32 v67, 0
	v_lshl_add_u64 v[68:69], v[66:67], 2, s[30:31]
	global_load_dword v67, v[68:69], off
	s_branch .Lc2_skip11

.LBB0_996:
	s_or_b64 exec, exec, s[38:39]
	s_waitcnt vmcnt(0)
	s_cmp_eq_u32 s101, 1
	s_mov_b32 s101, 0
	s_cbranch_scc0 .Lc2_slow11
	v_mov_b32_e32 v54, 1.0
	v_cndmask_b32_e64 v54, v54, v67, s[0:1]
	s_branch .Lc2_end11
.Lc2_slow11:
	v_add_u32_e32 v0, 32, v56
	v_cmp_gt_i32_e32 vcc, s64, v0
	v_mov_b32_e32 v54, 1.0
	v_mov_b32_e32 v27, 0
	v_mov_b32_e32 v26, 0
	v_mov_b32_e32 v25, 0
	v_mov_b32_e32 v24, 0
	s_and_saveexec_b64 s[38:39], vcc
	s_cbranch_execz .LBB0_1006
	v_cmp_gt_i32_e32 vcc, s70, v43
	v_mov_b32_e32 v24, 0
	v_mov_b32_e32 v25, 0
	v_mov_b32_e32 v26, 0
	v_mov_b32_e32 v27, 0
	s_and_saveexec_b64 s[40:41], vcc
	s_cbranch_execz .LBB0_999
	v_mad_i64_i32 v[2:3], s[78:79], v0, s70, 0
	v_lshl_add_u64 v[2:3], v[2:3], 2, s[10:11]
	v_lshl_add_u64 v[2:3], s[36:37], 2, v[2:3]
	v_lshlrev_b32_e32 v0, 2, v41
	v_lshl_add_u64 v[2:3], v[2:3], 0, v[0:1]
	global_load_dwordx4 v[24:27], v[2:3], off

.LBB0_1006:
	s_or_b64 exec, exec, s[38:39]
.Lc2_end11:
	s_and_b64 vcc, exec, s[4:5]
	s_cbranch_vccz .LBB0_870
.LBB0_1007:
	s_abs_i32 s77, s42
	s_waitcnt vmcnt(0)
	v_cvt_f32_u32_e32 v0, s77
	s_lshl_b32 s4, s44, 6
	s_lshl_b32 s5, s43, 6
	s_sub_i32 s36, 0, s77
	v_rcp_iflag_f32_e32 v0, v0
	s_sub_i32 s82, s4, s5
	s_lshl_b32 s79, s42, 6
	s_ashr_i32 s78, s42, 31
	v_mul_f32_e32 v0, 0x4f7ffffe, v0
	v_cvt_u32_f32_e32 v0, v0
	s_sub_i32 s84, 0, s79
	v_readfirstlane_b32 s4, v0
	s_mul_i32 s36, s36, s4
	s_mul_hi_u32 s5, s4, s36
	s_add_i32 s83, s4, s5

.LBB0_1021:
	s_or_b64 exec, exec, s[4:5]
	s_add_i32 s85, s76, s94
	s_waitcnt lgkmcnt(0)
	s_barrier
	s_cmp_ge_i32 s85, s67
	s_cselect_b64 s[4:5], -1, 0
	s_and_b64 vcc, exec, s[4:5]
	s_cbranch_vccnz .LBB0_1049
	s_abs_i32 s37, s85
	s_mul_hi_u32 s38, s37, s83
	s_mul_i32 s39, s38, s77
	s_ashr_i32 s36, s85, 31
	s_sub_i32 s37, s37, s39
	s_xor_b32 s36, s36, s78
	s_add_i32 s39, s38, 1
	s_sub_i32 s40, s37, s77
	s_cmp_ge_u32 s37, s77
	s_cselect_b32 s38, s39, s38
	s_cselect_b32 s37, s40, s37
	s_add_i32 s39, s38, 1
	s_cmp_ge_u32 s37, s77
	v_mov_b32_e32 v0, v202
	s_cselect_b32 s37, s39, s38
	s_xor_b32 s37, s37, s36
	s_sub_i32 s37, s37, s36
	v_ashrrev_i32_e32 v2, 4, v0
	v_lshlrev_b32_e32 v0, 2, v0
	s_mul_i32 s36, s84, s37
	v_and_b32_e32 v41, 60, v0
	v_lshl_add_u32 v56, s37, 6, v2
	s_mul_i32 s37, s79, s37
	s_add_i32 s38, s29, s82
	v_subrev_u32_e32 v0, s37, v41
	v_mov_b32_e32 v2, v1
	v_mov_b32_e32 v3, v1
	s_add_i32 s36, s38, s36
	v_add_u32_e32 v43, s38, v0
	v_mov_b32_e32 v0, v1
	v_mov_b64_e32 v[22:23], v[2:3]
	s_ashr_i32 s37, s36, 31
	v_cmp_gt_i32_e32 vcc, s64, v56
	v_mov_b32_e32 v46, 1.0
	v_mov_b64_e32 v[20:21], v[0:1]
	s_and_saveexec_b64 s[38:39], vcc
	s_cbranch_execz .LBB0_1035
	v_mov_b32_e32 v2, v1
	v_mov_b32_e32 v3, v1
	v_mov_b32_e32 v0, v1
	v_mov_b64_e32 v[22:23], v[2:3]
	v_cmp_gt_i32_e32 vcc, s70, v43
	v_mov_b64_e32 v[20:21], v[0:1]
	s_and_saveexec_b64 s[40:41], vcc
	s_cbranch_execz .LBB0_1025
	v_mad_i64_i32 v[2:3], s[42:43], v56, s70, 0
	v_lshl_add_u64 v[2:3], v[2:3], 2, s[10:11]
	v_lshl_add_u64 v[2:3], s[36:37], 2, v[2:3]
	v_lshlrev_b32_e32 v0, 2, v41
	v_lshl_add_u64 v[2:3], v[2:3], 0, v[0:1]
	global_load_dwordx4 v[20:23], v[2:3], off
	s_cmp_lt_i32 s64, 64
	s_cbranch_scc1 .Lc2_skip12
	s_and_b32 s100, s70, 63
	s_cmp_lg_u32 s100, 0
	s_cbranch_scc1 .Lc2_skip12
	s_lshl_b32 s100, s70, 7
	v_add_co_u32_e32 v70, vcc, s100, v2
	s_nop 1
	v_addc_co_u32_e32 v71, vcc, 0, v3, vcc
	s_cmp_lg_u32 s72, 0
	s_cbranch_scc1 .Lc2_pf12
	s_mov_b32 s101, 1
	global_load_dwordx4 v[36:39], v[70:71], off
	s_cmp_lg_u64 s[0:1], 0
	s_cbranch_scc0 .Lc2_skip12
	v_add_u32_e32 v66, 32, v56
	v_mov_b32_e32 v67, 0
	v_lshl_add_u64 v[68:69], v[66:67], 2, s[30:31]
	global_load_dword v67, v[68:69], off
	s_branch .Lc2_skip12

.Lc2_slow12:
	v_add_u32_e32 v0, 32, v56
	v_cmp_gt_i32_e32 vcc, s64, v0
	v_mov_b32_e32 v52, 1.0
	v_mov_b32_e32 v39, 0
	v_mov_b32_e32 v38, 0
	v_mov_b32_e32 v37, 0
	v_mov_b32_e32 v36, 0
	s_and_saveexec_b64 s[38:39], vcc
	s_cbranch_execz .LBB0_1048
	v_cmp_gt_i32_e32 vcc, s70, v43
	v_mov_b32_e32 v36, 0
	v_mov_b32_e32 v37, 0
	v_mov_b32_e32 v38, 0
	v_mov_b32_e32 v39, 0
	s_and_saveexec_b64 s[40:41], vcc
	s_cbranch_execz .LBB0_1038
	v_mad_i64_i32 v[2:3], s[42:43], v0, s70, 0
	v_lshl_add_u64 v[2:3], v[2:3], 2, s[10:11]
	v_lshl_add_u64 v[2:3], s[36:37], 2, v[2:3]
	v_lshlrev_b32_e32 v0, 2, v41
	v_lshl_add_u64 v[2:3], v[2:3], 0, v[0:1]
	global_load_dwordx4 v[36:39], v[2:3], off

.Lc2_end12:
.LBB0_1049:
	s_add_i32 s36, s28, s76
	s_cmp_ge_i32 s36, s67
	s_cbranch_scc1 .LBB0_1091
	s_ashr_i32 s37, s36, 31
	s_abs_i32 s36, s36
	s_mul_hi_u32 s38, s36, s83
	s_mul_i32 s39, s38, s77
	s_sub_i32 s36, s36, s39
	s_xor_b32 s37, s37, s78
	s_add_i32 s39, s38, 1
	s_sub_i32 s40, s36, s77
	s_waitcnt vmcnt(0)
	v_mov_b32_e32 v0, v202
	s_cmp_ge_u32 s36, s77
	s_cselect_b32 s38, s39, s38
	v_ashrrev_i32_e32 v2, 4, v0
	v_lshlrev_b32_e32 v3, 4, v0
	s_cselect_b32 s36, s40, s36
	s_add_i32 s39, s38, 1
	v_and_b32_e32 v3, 0xf0, v3
	v_mul_lo_u32 v2, v2, s3
	s_cmp_ge_u32 s36, s77
	v_add3_u32 v41, 0, v3, v2
	v_pk_mul_f32 v[2:3], v[44:45], v[16:17] op_sel_hi:[0,1]
	s_cselect_b32 s36, s39, s38
	ds_write2_b32 v41, v2, v3 offset1:1
	v_pk_mul_f32 v[2:3], v[44:45], v[18:19] op_sel_hi:[0,1]
	s_xor_b32 s36, s36, s37
	ds_write2_b32 v41, v2, v3 offset0:2 offset1:3
	v_add_u32_e32 v43, 0x2080, v41
	v_pk_mul_f32 v[2:3], v[50:51], v[32:33] op_sel_hi:[0,1]
	s_sub_i32 s38, s36, s37
	ds_write2_b32 v43, v2, v3 offset1:1
	v_add_u32_e32 v41, 0x2088, v41
	v_pk_mul_f32 v[2:3], v[50:51], v[34:35] op_sel_hi:[0,1]
	ds_write2_b32 v41, v2, v3 offset1:1
	v_ashrrev_i32_e32 v2, 3, v0
	s_mul_i32 s36, s79, s38
	s_waitcnt lgkmcnt(0)
	s_barrier
	v_subrev_u32_e32 v3, s36, v2
	s_add_i32 s36, s80, s82
	v_add_u32_e32 v41, s36, v3
	v_cmp_gt_i32_e32 vcc, s70, v41
	s_and_saveexec_b64 s[36:37], vcc
	s_cbranch_execz .LBB0_1063
	v_lshlrev_b32_e32 v0, 3, v0
	s_lshl_b32 s38, s38, 6
	v_and_b32_e32 v0, 56, v0
	v_or_b32_e32 v3, s38, v0
	v_cmp_gt_i32_e32 vcc, s65, v3
	s_and_b64 exec, exec, vcc
	s_cbranch_execz .LBB0_1063
	v_lshlrev_b32_e32 v45, 2, v2
	v_mul_u32_u24_e32 v2, 0x104, v0
	v_add3_u32 v43, 0, v45, v2
	ds_read2_b32 v[2:3], v43 offset1:65
	ds_read2_b32 v[56:57], v43 offset0:130 offset1:195
	v_add_u32_e32 v43, 0x400, v43
	ds_read2_b32 v[58:59], v43 offset0:4 offset1:69
	ds_read2_b32 v[60:61], v43 offset0:134 offset1:199
	s_mov_b64 s[44:45], -1
	s_mov_b64 s[40:41], 0
	s_cmp_lt_i32 s71, 2
	s_mov_b64 s[42:43], 0
	s_cbranch_scc1 .LBB0_1058
	s_cmp_eq_u32 s71, 2
	s_mov_b64 s[42:43], -1
	s_cbranch_scc0 .LBB0_1055
	v_and_b32_e32 v43, 0x80, v45
	v_lshrrev_b32_e32 v45, 1, v41
	v_and_b32_e32 v45, 0x60, v45
	v_and_b32_e32 v47, 0xffffff1f, v41
	v_or3_b32 v43, v47, v43, v45
	s_mov_b64 s[42:43], 0

.LBB0_1063:
	s_or_b64 exec, exec, s[36:37]
	s_waitcnt lgkmcnt(0)
	s_barrier
	s_mul_i32 s36, s28, 5
	s_add_i32 s36, s36, s76
	s_cmp_ge_i32 s36, s67
	s_cbranch_scc1 .LBB0_1091
	s_ashr_i32 s37, s36, 31
	s_abs_i32 s36, s36
	s_mul_hi_u32 s38, s36, s83
	s_mul_i32 s39, s38, s77
	s_sub_i32 s36, s36, s39
	s_xor_b32 s37, s37, s78
	s_add_i32 s39, s38, 1
	s_sub_i32 s40, s36, s77
	s_cmp_ge_u32 s36, s77
	s_cselect_b32 s38, s39, s38
	s_cselect_b32 s36, s40, s36
	s_add_i32 s39, s38, 1
	s_cmp_ge_u32 s36, s77
	v_mov_b32_e32 v0, v202
	s_cselect_b32 s36, s39, s38
	s_xor_b32 s36, s36, s37
	s_sub_i32 s37, s36, s37
	v_ashrrev_i32_e32 v2, 4, v0
	v_lshlrev_b32_e32 v0, 2, v0
	s_mul_i32 s36, s84, s37
	s_mul_i32 s38, s28, 0x140
	v_and_b32_e32 v41, 60, v0
	v_lshl_add_u32 v56, s37, 6, v2
	s_mul_i32 s37, s79, s37
	s_add_i32 s38, s38, s82
	v_subrev_u32_e32 v0, s37, v41
	v_mov_b32_e32 v2, v1
	v_mov_b32_e32 v3, v1
	s_add_i32 s36, s38, s36
	v_add_u32_e32 v43, s38, v0
	v_mov_b32_e32 v0, v1
	v_mov_b64_e32 v[18:19], v[2:3]
	s_ashr_i32 s37, s36, 31
	v_cmp_gt_i32_e32 vcc, s64, v56
	v_mov_b32_e32 v44, 1.0
	v_mov_b64_e32 v[16:17], v[0:1]
	s_and_saveexec_b64 s[38:39], vcc
	s_cbranch_execz .LBB0_1077
	v_mov_b32_e32 v2, v1
	v_mov_b32_e32 v3, v1
	v_mov_b32_e32 v0, v1
	v_mov_b64_e32 v[18:19], v[2:3]
	v_cmp_gt_i32_e32 vcc, s70, v43
	v_mov_b64_e32 v[16:17], v[0:1]
	s_and_saveexec_b64 s[40:41], vcc
	s_cbranch_execz .LBB0_1067
	v_mad_i64_i32 v[2:3], s[42:43], v56, s70, 0
	v_lshl_add_u64 v[2:3], v[2:3], 2, s[10:11]
	v_lshl_add_u64 v[2:3], s[36:37], 2, v[2:3]
	v_lshlrev_b32_e32 v0, 2, v41
	v_lshl_add_u64 v[2:3], v[2:3], 0, v[0:1]
	global_load_dwordx4 v[16:19], v[2:3], off
	s_cmp_lt_i32 s64, 64
	s_cbranch_scc1 .Lc2_skip13
	s_and_b32 s100, s70, 63
	s_cmp_lg_u32 s100, 0
	s_cbranch_scc1 .Lc2_skip13
	s_lshl_b32 s100, s70, 7
	v_add_co_u32_e32 v70, vcc, s100, v2
	s_nop 1
	v_addc_co_u32_e32 v71, vcc, 0, v3, vcc
	s_cmp_lg_u32 s72, 0
	s_cbranch_scc1 .Lc2_pf13
	s_mov_b32 s101, 1
	global_load_dwordx4 v[32:35], v[70:71], off
	s_cmp_lg_u64 s[0:1], 0
	s_cbranch_scc0 .Lc2_skip13
	v_add_u32_e32 v66, 32, v56
	v_mov_b32_e32 v67, 0
	v_lshl_add_u64 v[68:69], v[66:67], 2, s[30:31]
	global_load_dword v67, v[68:69], off
	s_branch .Lc2_skip13

.Lc2_slow13:
	v_add_u32_e32 v0, 32, v56
	v_cmp_gt_i32_e32 vcc, s64, v0
	v_mov_b32_e32 v50, 1.0
	v_mov_b32_e32 v35, 0
	v_mov_b32_e32 v34, 0
	v_mov_b32_e32 v33, 0
	v_mov_b32_e32 v32, 0
	s_and_saveexec_b64 s[38:39], vcc
	s_cbranch_execz .LBB0_1090
	v_cmp_gt_i32_e32 vcc, s70, v43
	v_mov_b32_e32 v32, 0
	v_mov_b32_e32 v33, 0
	v_mov_b32_e32 v34, 0
	v_mov_b32_e32 v35, 0
	s_and_saveexec_b64 s[40:41], vcc
	s_cbranch_execz .LBB0_1080
	v_mad_i64_i32 v[2:3], s[42:43], v0, s70, 0
	v_lshl_add_u64 v[2:3], v[2:3], 2, s[10:11]
	v_lshl_add_u64 v[2:3], s[36:37], 2, v[2:3]
	v_lshlrev_b32_e32 v0, 2, v41
	v_lshl_add_u64 v[2:3], v[2:3], 0, v[0:1]
	global_load_dwordx4 v[32:35], v[2:3], off

.Lc2_end13:
.LBB0_1091:
	s_add_i32 s36, s95, s76
	s_cmp_ge_i32 s36, s67
	s_cbranch_scc1 .LBB0_1133
	s_ashr_i32 s37, s36, 31
	s_abs_i32 s36, s36
	s_mul_hi_u32 s38, s36, s83
	s_mul_i32 s39, s38, s77
	s_sub_i32 s36, s36, s39
	s_waitcnt vmcnt(0)
	v_mov_b32_e32 v0, v202
	s_xor_b32 s37, s37, s78
	s_add_i32 s39, s38, 1
	s_sub_i32 s40, s36, s77
	s_cmp_ge_u32 s36, s77
	v_ashrrev_i32_e32 v2, 4, v0
	v_lshlrev_b32_e32 v3, 4, v0
	s_cselect_b32 s38, s39, s38
	v_and_b32_e32 v3, 0xf0, v3
	v_mul_lo_u32 v2, v2, s3
	s_cselect_b32 s36, s40, s36
	s_add_i32 s39, s38, 1
	v_add3_u32 v41, 0, v3, v2
	s_cmp_ge_u32 s36, s77
	v_pk_mul_f32 v[2:3], v[40:41], v[12:13] op_sel_hi:[0,1]
	s_cselect_b32 s36, s39, s38
	ds_write2_b32 v41, v2, v3 offset1:1
	v_pk_mul_f32 v[2:3], v[40:41], v[14:15] op_sel_hi:[0,1]
	s_xor_b32 s36, s36, s37
	ds_write2_b32 v41, v2, v3 offset0:2 offset1:3
	v_add_u32_e32 v43, 0x2080, v41
	v_pk_mul_f32 v[2:3], v[48:49], v[28:29] op_sel_hi:[0,1]
	s_sub_i32 s38, s36, s37
	ds_write2_b32 v43, v2, v3 offset1:1
	v_add_u32_e32 v41, 0x2088, v41
	v_pk_mul_f32 v[2:3], v[48:49], v[30:31] op_sel_hi:[0,1]
	ds_write2_b32 v41, v2, v3 offset1:1
	v_ashrrev_i32_e32 v2, 3, v0
	s_mul_i32 s36, s79, s38
	s_waitcnt lgkmcnt(0)
	s_barrier
	v_subrev_u32_e32 v3, s36, v2
	s_add_i32 s36, s81, s82
	v_add_u32_e32 v41, s36, v3
	v_cmp_gt_i32_e32 vcc, s70, v41
	s_and_saveexec_b64 s[36:37], vcc
	s_cbranch_execz .LBB0_1105
	v_lshlrev_b32_e32 v0, 3, v0
	s_lshl_b32 s38, s38, 6
	v_and_b32_e32 v0, 56, v0
	v_or_b32_e32 v3, s38, v0
	v_cmp_gt_i32_e32 vcc, s65, v3
	s_and_b64 exec, exec, vcc
	s_cbranch_execz .LBB0_1105
	v_lshlrev_b32_e32 v45, 2, v2
	v_mul_u32_u24_e32 v2, 0x104, v0
	v_add3_u32 v43, 0, v45, v2
	ds_read2_b32 v[2:3], v43 offset1:65
	ds_read2_b32 v[56:57], v43 offset0:130 offset1:195
	v_add_u32_e32 v43, 0x400, v43
	ds_read2_b32 v[58:59], v43 offset0:4 offset1:69
	ds_read2_b32 v[60:61], v43 offset0:134 offset1:199
	s_mov_b64 s[44:45], -1
	s_mov_b64 s[40:41], 0
	s_cmp_lt_i32 s71, 2
	s_mov_b64 s[42:43], 0
	s_cbranch_scc1 .LBB0_1100
	s_cmp_eq_u32 s71, 2
	s_mov_b64 s[42:43], -1
	s_cbranch_scc0 .LBB0_1097
	v_and_b32_e32 v43, 0x80, v45
	v_lshrrev_b32_e32 v45, 1, v41
	v_and_b32_e32 v45, 0x60, v45
	v_and_b32_e32 v47, 0xffffff1f, v41
	v_or3_b32 v43, v47, v43, v45
	s_mov_b64 s[42:43], 0

.LBB0_1105:
	s_or_b64 exec, exec, s[36:37]
	s_waitcnt lgkmcnt(0)
	s_barrier
	s_mul_i32 s36, s28, 6
	s_add_i32 s36, s36, s76
	s_cmp_ge_i32 s36, s67
	s_cbranch_scc1 .LBB0_1133
	s_ashr_i32 s37, s36, 31
	s_abs_i32 s36, s36
	s_mul_hi_u32 s38, s36, s83
	s_mul_i32 s39, s38, s77
	s_sub_i32 s36, s36, s39
	s_xor_b32 s37, s37, s78
	s_add_i32 s39, s38, 1
	s_sub_i32 s40, s36, s77
	s_cmp_ge_u32 s36, s77
	s_cselect_b32 s38, s39, s38
	s_cselect_b32 s36, s40, s36
	s_add_i32 s39, s38, 1
	s_cmp_ge_u32 s36, s77
	v_mov_b32_e32 v0, v202
	s_cselect_b32 s36, s39, s38
	s_xor_b32 s36, s36, s37
	s_sub_i32 s37, s36, s37
	v_ashrrev_i32_e32 v2, 4, v0
	v_lshlrev_b32_e32 v0, 2, v0
	s_mul_i32 s36, s84, s37
	s_mul_i32 s38, s28, 0x180
	v_and_b32_e32 v41, 60, v0
	v_lshl_add_u32 v56, s37, 6, v2
	s_mul_i32 s37, s79, s37
	s_add_i32 s38, s38, s82
	v_subrev_u32_e32 v0, s37, v41
	v_mov_b32_e32 v2, v1
	v_mov_b32_e32 v3, v1
	s_add_i32 s36, s38, s36
	v_add_u32_e32 v43, s38, v0
	v_mov_b32_e32 v0, v1
	v_mov_b64_e32 v[14:15], v[2:3]
	s_ashr_i32 s37, s36, 31
	v_cmp_gt_i32_e32 vcc, s64, v56
	v_mov_b32_e32 v40, 1.0
	v_mov_b64_e32 v[12:13], v[0:1]
	s_and_saveexec_b64 s[38:39], vcc
	s_cbranch_execz .LBB0_1119
	v_mov_b32_e32 v2, v1
	v_mov_b32_e32 v3, v1
	v_mov_b32_e32 v0, v1
	v_mov_b64_e32 v[14:15], v[2:3]
	v_cmp_gt_i32_e32 vcc, s70, v43
	v_mov_b64_e32 v[12:13], v[0:1]
	s_and_saveexec_b64 s[40:41], vcc
	s_cbranch_execz .LBB0_1109
	v_mad_i64_i32 v[2:3], s[42:43], v56, s70, 0
	v_lshl_add_u64 v[2:3], v[2:3], 2, s[10:11]
	v_lshl_add_u64 v[2:3], s[36:37], 2, v[2:3]
	v_lshlrev_b32_e32 v0, 2, v41
	v_lshl_add_u64 v[2:3], v[2:3], 0, v[0:1]
	global_load_dwordx4 v[12:15], v[2:3], off
	s_cmp_lt_i32 s64, 64
	s_cbranch_scc1 .Lc2_skip14
	s_and_b32 s100, s70, 63
	s_cmp_lg_u32 s100, 0
	s_cbranch_scc1 .Lc2_skip14
	s_lshl_b32 s100, s70, 7
	v_add_co_u32_e32 v70, vcc, s100, v2
	s_nop 1
	v_addc_co_u32_e32 v71, vcc, 0, v3, vcc
	s_cmp_lg_u32 s72, 0
	s_cbranch_scc1 .Lc2_pf14
	s_mov_b32 s101, 1
	global_load_dwordx4 v[28:31], v[70:71], off
	s_cmp_lg_u64 s[0:1], 0
	s_cbranch_scc0 .Lc2_skip14
	v_add_u32_e32 v66, 32, v56
	v_mov_b32_e32 v67, 0
	v_lshl_add_u64 v[68:69], v[66:67], 2, s[30:31]
	global_load_dword v67, v[68:69], off
	s_branch .Lc2_skip14

.Lc2_slow14:
	v_add_u32_e32 v0, 32, v56
	v_cmp_gt_i32_e32 vcc, s64, v0
	v_mov_b32_e32 v48, 1.0
	v_mov_b32_e32 v31, 0
	v_mov_b32_e32 v30, 0
	v_mov_b32_e32 v29, 0
	v_mov_b32_e32 v28, 0
	s_and_saveexec_b64 s[38:39], vcc
	s_cbranch_execz .LBB0_1132
	v_cmp_gt_i32_e32 vcc, s70, v43
	v_mov_b32_e32 v28, 0
	v_mov_b32_e32 v29, 0
	v_mov_b32_e32 v30, 0
	v_mov_b32_e32 v31, 0
	s_and_saveexec_b64 s[40:41], vcc
	s_cbranch_execz .LBB0_1122
	v_mad_i64_i32 v[2:3], s[42:43], v0, s70, 0
	v_lshl_add_u64 v[2:3], v[2:3], 2, s[10:11]
	v_lshl_add_u64 v[2:3], s[36:37], 2, v[2:3]
	v_lshlrev_b32_e32 v0, 2, v41
	v_lshl_add_u64 v[2:3], v[2:3], 0, v[0:1]
	global_load_dwordx4 v[28:31], v[2:3], off

.Lc2_end14:
.LBB0_1133:
	s_add_i32 s36, s33, s76
	s_cmp_ge_i32 s36, s67
	s_cbranch_scc1 .LBB0_1175
	s_ashr_i32 s37, s36, 31
	s_abs_i32 s36, s36
	s_mul_hi_u32 s38, s36, s83
	s_mul_i32 s39, s38, s77
	s_sub_i32 s36, s36, s39
	s_xor_b32 s37, s37, s78
	s_add_i32 s39, s38, 1
	s_sub_i32 s40, s36, s77
	s_waitcnt vmcnt(0)
	v_mov_b32_e32 v0, v202
	s_cmp_ge_u32 s36, s77
	s_cselect_b32 s38, s39, s38
	v_ashrrev_i32_e32 v2, 4, v0
	v_lshlrev_b32_e32 v3, 4, v0
	s_cselect_b32 s36, s40, s36
	s_add_i32 s39, s38, 1
	v_and_b32_e32 v3, 0xf0, v3
	v_mul_lo_u32 v2, v2, s3
	s_cmp_ge_u32 s36, s77
	v_add3_u32 v41, 0, v3, v2
	s_waitcnt lgkmcnt(4)
	v_pk_mul_f32 v[2:3], v[8:9], v[42:43] op_sel_hi:[1,0]
	s_cselect_b32 s36, s39, s38
	ds_write2_b32 v41, v2, v3 offset1:1
	v_pk_mul_f32 v[2:3], v[10:11], v[42:43] op_sel_hi:[1,0]
	s_xor_b32 s36, s36, s37
	ds_write2_b32 v41, v2, v3 offset0:2 offset1:3
	v_add_u32_e32 v43, 0x2080, v41
	v_pk_mul_f32 v[2:3], v[24:25], v[54:55] op_sel_hi:[1,0]
	s_sub_i32 s38, s36, s37
	ds_write2_b32 v43, v2, v3 offset1:1
	v_add_u32_e32 v41, 0x2088, v41
	v_pk_mul_f32 v[2:3], v[26:27], v[54:55] op_sel_hi:[1,0]
	ds_write2_b32 v41, v2, v3 offset1:1
	v_ashrrev_i32_e32 v2, 3, v0
	s_mul_i32 s36, s79, s38
	v_subrev_u32_e32 v3, s36, v2
	s_mul_i32 s36, s28, 0xc0
	s_waitcnt lgkmcnt(0)
	s_barrier
	s_add_i32 s36, s36, s82
	v_add_u32_e32 v41, s36, v3
	v_cmp_gt_i32_e32 vcc, s70, v41
	s_and_saveexec_b64 s[36:37], vcc
	s_cbranch_execz .LBB0_1147
	v_lshlrev_b32_e32 v0, 3, v0
	s_lshl_b32 s38, s38, 6
	v_and_b32_e32 v0, 56, v0
	v_or_b32_e32 v3, s38, v0
	v_cmp_gt_i32_e32 vcc, s65, v3
	s_and_b64 exec, exec, vcc
	s_cbranch_execz .LBB0_1147
	v_lshlrev_b32_e32 v45, 2, v2
	v_mul_u32_u24_e32 v2, 0x104, v0
	v_add3_u32 v43, 0, v45, v2
	ds_read2_b32 v[2:3], v43 offset1:65
	ds_read2_b32 v[56:57], v43 offset0:130 offset1:195
	v_add_u32_e32 v43, 0x400, v43
	ds_read2_b32 v[58:59], v43 offset0:4 offset1:69
	ds_read2_b32 v[60:61], v43 offset0:134 offset1:199
	s_mov_b64 s[44:45], -1
	s_mov_b64 s[40:41], 0
	s_cmp_lt_i32 s71, 2
	s_mov_b64 s[42:43], 0
	s_cbranch_scc1 .LBB0_1142
	s_cmp_eq_u32 s71, 2
	s_mov_b64 s[42:43], -1
	s_cbranch_scc0 .LBB0_1139
	v_and_b32_e32 v43, 0x80, v45
	v_lshrrev_b32_e32 v45, 1, v41
	v_and_b32_e32 v45, 0x60, v45
	v_and_b32_e32 v47, 0xffffff1f, v41
	v_or3_b32 v43, v47, v43, v45
	s_mov_b64 s[42:43], 0

.LBB0_1147:
	s_or_b64 exec, exec, s[36:37]
	s_waitcnt lgkmcnt(0)
	s_barrier
	s_mul_i32 s36, s28, 7
	s_add_i32 s36, s36, s76
	s_cmp_ge_i32 s36, s67
	s_cbranch_scc1 .LBB0_1175
	s_ashr_i32 s37, s36, 31
	s_abs_i32 s36, s36
	s_mul_hi_u32 s38, s36, s83
	s_mul_i32 s39, s38, s77
	s_sub_i32 s36, s36, s39
	s_xor_b32 s37, s37, s78
	s_add_i32 s39, s38, 1
	s_sub_i32 s40, s36, s77
	s_cmp_ge_u32 s36, s77
	s_cselect_b32 s38, s39, s38
	s_cselect_b32 s36, s40, s36
	s_add_i32 s39, s38, 1
	s_cmp_ge_u32 s36, s77
	v_mov_b32_e32 v0, v202
	s_cselect_b32 s36, s39, s38
	s_xor_b32 s36, s36, s37
	s_sub_i32 s37, s36, s37
	v_ashrrev_i32_e32 v2, 4, v0
	v_lshlrev_b32_e32 v0, 2, v0
	s_mul_i32 s36, s84, s37
	s_mul_i32 s38, s28, 0x1c0
	v_and_b32_e32 v41, 60, v0
	v_lshl_add_u32 v56, s37, 6, v2
	s_mul_i32 s37, s79, s37
	s_add_i32 s38, s38, s82
	v_subrev_u32_e32 v0, s37, v41
	v_mov_b32_e32 v2, v1
	v_mov_b32_e32 v3, v1
	s_add_i32 s36, s38, s36
	v_add_u32_e32 v43, s38, v0
	v_mov_b32_e32 v0, v1
	v_mov_b64_e32 v[10:11], v[2:3]
	s_ashr_i32 s37, s36, 31
	v_cmp_gt_i32_e32 vcc, s64, v56
	v_mov_b32_e32 v42, 1.0
	v_mov_b64_e32 v[8:9], v[0:1]
	s_and_saveexec_b64 s[38:39], vcc
	s_cbranch_execz .LBB0_1161
	v_mov_b32_e32 v2, v1
	v_mov_b32_e32 v3, v1
	v_mov_b32_e32 v0, v1
	v_mov_b64_e32 v[10:11], v[2:3]
	v_cmp_gt_i32_e32 vcc, s70, v43
	v_mov_b64_e32 v[8:9], v[0:1]
	s_and_saveexec_b64 s[40:41], vcc
	s_cbranch_execz .LBB0_1151
	v_mad_i64_i32 v[2:3], s[42:43], v56, s70, 0
	v_lshl_add_u64 v[2:3], v[2:3], 2, s[10:11]
	v_lshl_add_u64 v[2:3], s[36:37], 2, v[2:3]
	v_lshlrev_b32_e32 v0, 2, v41
	v_lshl_add_u64 v[2:3], v[2:3], 0, v[0:1]
	global_load_dwordx4 v[8:11], v[2:3], off
	s_cmp_lt_i32 s64, 64
	s_cbranch_scc1 .Lc2_skip15
	s_and_b32 s100, s70, 63
	s_cmp_lg_u32 s100, 0
	s_cbranch_scc1 .Lc2_skip15
	s_lshl_b32 s100, s70, 7
	v_add_co_u32_e32 v70, vcc, s100, v2
	s_nop 1
	v_addc_co_u32_e32 v71, vcc, 0, v3, vcc
	s_cmp_lg_u32 s72, 0
	s_cbranch_scc1 .Lc2_pf15
	s_mov_b32 s101, 1
	global_load_dwordx4 v[24:27], v[70:71], off
	s_cmp_lg_u64 s[0:1], 0
	s_cbranch_scc0 .Lc2_skip15
	v_add_u32_e32 v66, 32, v56
	v_mov_b32_e32 v67, 0
	v_lshl_add_u64 v[68:69], v[66:67], 2, s[30:31]
	global_load_dword v67, v[68:69], off
	s_branch .Lc2_skip15

.Lc2_slow15:
	v_add_u32_e32 v0, 32, v56
	v_cmp_gt_i32_e32 vcc, s64, v0
	v_mov_b32_e32 v54, 1.0
	v_mov_b32_e32 v27, 0
	v_mov_b32_e32 v26, 0
	v_mov_b32_e32 v25, 0
	v_mov_b32_e32 v24, 0
	s_and_saveexec_b64 s[38:39], vcc
	s_cbranch_execz .LBB0_1174
	v_cmp_gt_i32_e32 vcc, s70, v43
	v_mov_b32_e32 v24, 0
	v_mov_b32_e32 v25, 0
	v_mov_b32_e32 v26, 0
	v_mov_b32_e32 v27, 0
	s_and_saveexec_b64 s[40:41], vcc
	s_cbranch_execz .LBB0_1164
	v_mad_i64_i32 v[2:3], s[42:43], v0, s70, 0
	v_lshl_add_u64 v[2:3], v[2:3], 2, s[10:11]
	v_lshl_add_u64 v[2:3], s[36:37], 2, v[2:3]
	v_lshlrev_b32_e32 v0, 2, v41
	v_lshl_add_u64 v[2:3], v[2:3], 0, v[0:1]
	global_load_dwordx4 v[24:27], v[2:3], off

.Lc2_end15:
.LBB0_1175:
	s_andn2_b64 vcc, exec, s[4:5]
	s_add_i32 s82, s82, s29
	s_cbranch_vccz .LBB0_869
	s_mov_b32 s76, s85
	s_branch .LBB0_1008

.LBB0_1270:
	s_add_i32 s30, s64, 63
	s_lshr_b32 s72, s30, 6
	s_add_i32 s30, s68, 63
	s_ashr_i32 s42, s30, 6
	s_mul_i32 s30, s67, 37
	s_add_i32 s30, s30, s66
	s_ashr_i32 s43, s30, 31
	s_abs_i32 s30, s30
	v_readlane_b32 s31, v252, 1
	s_mul_hi_u32 s31, s30, s31
	v_readlane_b32 s34, v252, 0
	s_mul_i32 s31, s31, s34
	s_sub_i32 s30, s30, s31
	s_sub_i32 s31, s30, s34
	s_cmp_ge_u32 s30, s34
	s_cselect_b32 s30, s31, s30
	s_sub_i32 s31, s30, s34
	s_cmp_ge_u32 s30, s34
	s_cselect_b32 s30, s31, s30
	s_xor_b32 s44, s30, s43
	s_sub_i32 s76, s44, s43
	s_mul_i32 s72, s72, s42
	s_cmp_lg_u64 s[8:9], 0
	s_cselect_b64 s[30:31], -1, 0
	s_cmp_lt_i32 s76, s72
	s_cselect_b64 s[34:35], -1, 0
	s_and_b64 vcc, exec, s[34:35]
	s_cbranch_vccz .LBB0_1315
	s_abs_i32 s36, s42
	v_cvt_f32_u32_e32 v0, s36
	s_sub_i32 s39, 0, s36
	s_abs_i32 s38, s76
	s_xor_b32 s37, s76, s42
	v_rcp_iflag_f32_e32 v0, v0
	s_ashr_i32 s37, s37, 31
	v_mov_b32_e32 v2, v202
	v_mul_f32_e32 v0, 0x4f7ffffe, v0
	v_cvt_u32_f32_e32 v0, v0
	v_ashrrev_i32_e32 v3, 4, v2
	v_mov_b32_e32 v46, 1.0
	v_readfirstlane_b32 s40, v0
	s_mul_i32 s39, s39, s40
	s_mul_hi_u32 s39, s40, s39
	s_add_i32 s40, s40, s39
	s_mul_hi_u32 s39, s38, s40
	s_mul_i32 s40, s39, s36
	s_sub_i32 s38, s38, s40
	s_add_i32 s41, s39, 1
	s_sub_i32 s40, s38, s36
	s_cmp_ge_u32 s38, s36
	s_cselect_b32 s39, s41, s39
	s_cselect_b32 s38, s40, s38
	s_add_i32 s40, s39, 1
	s_cmp_ge_u32 s38, s36
	s_cselect_b32 s36, s40, s39
	s_xor_b32 s36, s36, s37
	s_sub_i32 s37, s36, s37
	s_mul_i32 s36, s37, s42
	s_sub_i32 s36, s76, s36
	v_lshlrev_b32_e32 v0, 2, v2
	v_lshl_add_u32 v56, s37, 6, v3
	v_mov_b32_e32 v2, v1
	v_mov_b32_e32 v3, v1
	s_lshl_b32 s36, s36, 6
	v_and_b32_e32 v41, 60, v0
	v_mov_b32_e32 v0, v1
	v_mov_b64_e32 v[22:23], v[2:3]
	v_or_b32_e32 v43, s36, v41
	s_ashr_i32 s37, s36, 31
	v_cmp_gt_i32_e32 vcc, s64, v56
	v_mov_b64_e32 v[20:21], v[0:1]
	s_and_saveexec_b64 s[38:39], vcc
	s_cbranch_execz .LBB0_1281
	v_mov_b32_e32 v2, v1
	v_mov_b32_e32 v3, v1
	v_mov_b32_e32 v0, v1
	v_mov_b64_e32 v[22:23], v[2:3]
	v_cmp_gt_i32_e32 vcc, s68, v43
	v_mov_b64_e32 v[20:21], v[0:1]
	s_and_saveexec_b64 s[40:41], vcc
	s_cbranch_execz .LBB0_1274
	v_mad_i64_i32 v[2:3], s[78:79], v56, s68, 0
	v_lshl_add_u64 v[2:3], v[2:3], 2, s[4:5]
	v_lshl_add_u64 v[2:3], s[36:37], 2, v[2:3]
	v_lshlrev_b32_e32 v0, 2, v41
	v_lshl_add_u64 v[2:3], v[2:3], 0, v[0:1]
	global_load_dwordx4 v[20:23], v[2:3], off
	s_cmp_lt_i32 s64, 64
	s_cbranch_scc1 .Lc2_skip16
	s_and_b32 s100, s68, 63
	s_cmp_lg_u32 s100, 0
	s_cbranch_scc1 .Lc2_skip16
	s_lshl_b32 s100, s68, 7
	v_add_co_u32_e32 v70, vcc, s100, v2
	s_nop 1
	v_addc_co_u32_e32 v71, vcc, 0, v3, vcc
	s_cmp_lg_u32 s70, 0
	s_cbranch_scc1 .Lc2_pf16
	s_mov_b32 s101, 1
	global_load_dwordx4 v[36:39], v[70:71], off
	s_cmp_lg_u64 s[30:31], 0
	s_cbranch_scc0 .Lc2_skip16
	v_add_u32_e32 v66, 32, v56
	v_mov_b32_e32 v67, 0
	v_lshl_add_u64 v[68:69], v[66:67], 2, s[8:9]
	global_load_dword v67, v[68:69], off
	s_branch .Lc2_skip16

.LBB0_1281:
	s_or_b64 exec, exec, s[38:39]
	s_waitcnt vmcnt(0)
	s_cmp_eq_u32 s101, 1
	s_mov_b32 s101, 0
	s_cbranch_scc0 .Lc2_slow16
	v_mov_b32_e32 v52, 1.0
	v_cndmask_b32_e64 v52, v52, v67, s[30:31]
	s_branch .Lc2_end16
.Lc2_slow16:
	v_add_u32_e32 v0, 32, v56
	v_cmp_gt_i32_e32 vcc, s64, v0
	v_mov_b32_e32 v52, 1.0
	v_mov_b32_e32 v39, 0
	v_mov_b32_e32 v38, 0
	v_mov_b32_e32 v37, 0
	v_mov_b32_e32 v36, 0
	s_and_saveexec_b64 s[38:39], vcc
	s_cbranch_execz .LBB0_1291
	v_cmp_gt_i32_e32 vcc, s68, v43
	v_mov_b32_e32 v36, 0
	v_mov_b32_e32 v37, 0
	v_mov_b32_e32 v38, 0
	v_mov_b32_e32 v39, 0
	s_and_saveexec_b64 s[40:41], vcc
	s_cbranch_execz .LBB0_1284
	v_mad_i64_i32 v[2:3], s[78:79], v0, s68, 0
	v_lshl_add_u64 v[2:3], v[2:3], 2, s[4:5]
	v_lshl_add_u64 v[2:3], s[36:37], 2, v[2:3]
	v_lshlrev_b32_e32 v0, 2, v41
	v_lshl_add_u64 v[2:3], v[2:3], 0, v[0:1]
	global_load_dwordx4 v[36:39], v[2:3], off

.Lc2_end16:
	s_add_i32 s45, s76, s28
	s_cmp_ge_i32 s45, s72
	s_cbranch_scc0 .LBB0_1316

.LBB0_1293:
	s_abs_i32 s36, s42
	s_waitcnt vmcnt(0)
	v_cvt_f32_u32_e32 v0, s36
	s_sub_i32 s39, 0, s36
	s_abs_i32 s38, s45
	s_xor_b32 s37, s45, s42
	v_rcp_iflag_f32_e32 v0, v0
	s_ashr_i32 s37, s37, 31
	v_mov_b32_e32 v2, v202
	v_mul_f32_e32 v0, 0x4f7ffffe, v0
	v_cvt_u32_f32_e32 v0, v0
	v_ashrrev_i32_e32 v3, 4, v2
	v_mov_b32_e32 v40, 1.0
	v_readfirstlane_b32 s40, v0
	s_mul_i32 s39, s39, s40
	s_mul_hi_u32 s39, s40, s39
	s_add_i32 s40, s40, s39
	s_mul_hi_u32 s39, s38, s40
	s_mul_i32 s40, s39, s36
	s_sub_i32 s38, s38, s40
	s_add_i32 s41, s39, 1
	s_sub_i32 s40, s38, s36
	s_cmp_ge_u32 s38, s36
	s_cselect_b32 s39, s41, s39
	s_cselect_b32 s38, s40, s38
	s_add_i32 s40, s39, 1
	s_cmp_ge_u32 s38, s36
	s_cselect_b32 s36, s40, s39
	s_xor_b32 s36, s36, s37
	s_sub_i32 s37, s36, s37
	s_mul_i32 s36, s37, s42
	s_sub_i32 s36, s45, s36
	v_lshlrev_b32_e32 v0, 2, v2
	v_lshl_add_u32 v56, s37, 6, v3
	v_mov_b32_e32 v2, v1
	v_mov_b32_e32 v3, v1
	s_lshl_b32 s36, s36, 6
	v_and_b32_e32 v41, 60, v0
	v_mov_b32_e32 v0, v1
	v_mov_b64_e32 v[14:15], v[2:3]
	v_or_b32_e32 v43, s36, v41
	s_ashr_i32 s37, s36, 31
	v_cmp_gt_i32_e32 vcc, s64, v56
	v_mov_b64_e32 v[12:13], v[0:1]
	s_and_saveexec_b64 s[38:39], vcc
	s_cbranch_execz .LBB0_1303
	v_mov_b32_e32 v2, v1
	v_mov_b32_e32 v3, v1
	v_mov_b32_e32 v0, v1
	v_mov_b64_e32 v[14:15], v[2:3]
	v_cmp_gt_i32_e32 vcc, s68, v43
	v_mov_b64_e32 v[12:13], v[0:1]
	s_and_saveexec_b64 s[40:41], vcc
	s_cbranch_execz .LBB0_1296
	v_mad_i64_i32 v[2:3], s[78:79], v56, s68, 0
	v_lshl_add_u64 v[2:3], v[2:3], 2, s[4:5]
	v_lshl_add_u64 v[2:3], s[36:37], 2, v[2:3]
	v_lshlrev_b32_e32 v0, 2, v41
	v_lshl_add_u64 v[2:3], v[2:3], 0, v[0:1]
	global_load_dwordx4 v[12:15], v[2:3], off
	s_cmp_lt_i32 s64, 64
	s_cbranch_scc1 .Lc2_skip17
	s_and_b32 s100, s68, 63
	s_cmp_lg_u32 s100, 0
	s_cbranch_scc1 .Lc2_skip17
	s_lshl_b32 s100, s68, 7
	v_add_co_u32_e32 v70, vcc, s100, v2
	s_nop 1
	v_addc_co_u32_e32 v71, vcc, 0, v3, vcc
	s_cmp_lg_u32 s70, 0
	s_cbranch_scc1 .Lc2_pf17
	s_mov_b32 s101, 1
	global_load_dwordx4 v[28:31], v[70:71], off
	s_cmp_lg_u64 s[30:31], 0
	s_cbranch_scc0 .Lc2_skip17
	v_add_u32_e32 v66, 32, v56
	v_mov_b32_e32 v67, 0
	v_lshl_add_u64 v[68:69], v[66:67], 2, s[8:9]
	global_load_dword v67, v[68:69], off
	s_branch .Lc2_skip17

.LBB0_1303:
	s_or_b64 exec, exec, s[38:39]
	s_waitcnt vmcnt(0)
	s_cmp_eq_u32 s101, 1
	s_mov_b32 s101, 0
	s_cbranch_scc0 .Lc2_slow17
	v_mov_b32_e32 v48, 1.0
	v_cndmask_b32_e64 v48, v48, v67, s[30:31]
	s_branch .Lc2_end17
.Lc2_slow17:
	v_add_u32_e32 v0, 32, v56
	v_cmp_gt_i32_e32 vcc, s64, v0
	v_mov_b32_e32 v48, 1.0
	v_mov_b32_e32 v31, 0
	v_mov_b32_e32 v30, 0
	v_mov_b32_e32 v29, 0
	v_mov_b32_e32 v28, 0
	s_and_saveexec_b64 s[38:39], vcc
	s_cbranch_execz .LBB0_1313
	v_cmp_gt_i32_e32 vcc, s68, v43
	v_mov_b32_e32 v28, 0
	v_mov_b32_e32 v29, 0
	v_mov_b32_e32 v30, 0
	v_mov_b32_e32 v31, 0
	s_and_saveexec_b64 s[40:41], vcc
	s_cbranch_execz .LBB0_1306
	v_mad_i64_i32 v[2:3], s[78:79], v0, s68, 0
	v_lshl_add_u64 v[2:3], v[2:3], 2, s[4:5]
	v_lshl_add_u64 v[2:3], s[36:37], 2, v[2:3]
	v_lshlrev_b32_e32 v0, 2, v41
	v_lshl_add_u64 v[2:3], v[2:3], 0, v[0:1]
	global_load_dwordx4 v[28:31], v[2:3], off

.Lc2_end17:
	s_add_i32 s45, s45, s28
	s_cmp_ge_i32 s45, s72
	s_cbranch_scc0 .LBB0_1338

.LBB0_1316:
	s_abs_i32 s36, s42
	s_waitcnt vmcnt(0)
	v_cvt_f32_u32_e32 v0, s36
	s_sub_i32 s39, 0, s36
	s_abs_i32 s38, s45
	s_xor_b32 s37, s45, s42
	v_rcp_iflag_f32_e32 v0, v0
	s_ashr_i32 s37, s37, 31
	v_mov_b32_e32 v2, v202
	v_mul_f32_e32 v0, 0x4f7ffffe, v0
	v_cvt_u32_f32_e32 v0, v0
	v_ashrrev_i32_e32 v3, 4, v2
	v_mov_b32_e32 v44, 1.0
	v_readfirstlane_b32 s40, v0
	s_mul_i32 s39, s39, s40
	s_mul_hi_u32 s39, s40, s39
	s_add_i32 s40, s40, s39
	s_mul_hi_u32 s39, s38, s40
	s_mul_i32 s40, s39, s36
	s_sub_i32 s38, s38, s40
	s_add_i32 s41, s39, 1
	s_sub_i32 s40, s38, s36
	s_cmp_ge_u32 s38, s36
	s_cselect_b32 s39, s41, s39
	s_cselect_b32 s38, s40, s38
	s_add_i32 s40, s39, 1
	s_cmp_ge_u32 s38, s36
	s_cselect_b32 s36, s40, s39
	s_xor_b32 s36, s36, s37
	s_sub_i32 s37, s36, s37
	s_mul_i32 s36, s37, s42
	s_sub_i32 s36, s45, s36
	v_lshlrev_b32_e32 v0, 2, v2
	v_lshl_add_u32 v56, s37, 6, v3
	v_mov_b32_e32 v2, v1
	v_mov_b32_e32 v3, v1
	s_lshl_b32 s36, s36, 6
	v_and_b32_e32 v41, 60, v0
	v_mov_b32_e32 v0, v1
	v_mov_b64_e32 v[18:19], v[2:3]
	v_or_b32_e32 v43, s36, v41
	s_ashr_i32 s37, s36, 31
	v_cmp_gt_i32_e32 vcc, s64, v56
	v_mov_b64_e32 v[16:17], v[0:1]
	s_and_saveexec_b64 s[38:39], vcc
	s_cbranch_execz .LBB0_1326
	v_mov_b32_e32 v2, v1
	v_mov_b32_e32 v3, v1
	v_mov_b32_e32 v0, v1
	v_mov_b64_e32 v[18:19], v[2:3]
	v_cmp_gt_i32_e32 vcc, s68, v43
	v_mov_b64_e32 v[16:17], v[0:1]
	s_and_saveexec_b64 s[40:41], vcc
	s_cbranch_execz .LBB0_1319
	v_mad_i64_i32 v[2:3], s[78:79], v56, s68, 0
	v_lshl_add_u64 v[2:3], v[2:3], 2, s[4:5]
	v_lshl_add_u64 v[2:3], s[36:37], 2, v[2:3]
	v_lshlrev_b32_e32 v0, 2, v41
	v_lshl_add_u64 v[2:3], v[2:3], 0, v[0:1]
	global_load_dwordx4 v[16:19], v[2:3], off
	s_cmp_lt_i32 s64, 64
	s_cbranch_scc1 .Lc2_skip18
	s_and_b32 s100, s68, 63
	s_cmp_lg_u32 s100, 0
	s_cbranch_scc1 .Lc2_skip18
	s_lshl_b32 s100, s68, 7
	v_add_co_u32_e32 v70, vcc, s100, v2
	s_nop 1
	v_addc_co_u32_e32 v71, vcc, 0, v3, vcc
	s_cmp_lg_u32 s70, 0
	s_cbranch_scc1 .Lc2_pf18
	s_mov_b32 s101, 1
	global_load_dwordx4 v[32:35], v[70:71], off
	s_cmp_lg_u64 s[30:31], 0
	s_cbranch_scc0 .Lc2_skip18
	v_add_u32_e32 v66, 32, v56
	v_mov_b32_e32 v67, 0
	v_lshl_add_u64 v[68:69], v[66:67], 2, s[8:9]
	global_load_dword v67, v[68:69], off
	s_branch .Lc2_skip18

.LBB0_1326:
	s_or_b64 exec, exec, s[38:39]
	s_waitcnt vmcnt(0)
	s_cmp_eq_u32 s101, 1
	s_mov_b32 s101, 0
	s_cbranch_scc0 .Lc2_slow18
	v_mov_b32_e32 v50, 1.0
	v_cndmask_b32_e64 v50, v50, v67, s[30:31]
	s_branch .Lc2_end18
.Lc2_slow18:
	v_add_u32_e32 v0, 32, v56
	v_cmp_gt_i32_e32 vcc, s64, v0
	v_mov_b32_e32 v50, 1.0
	v_mov_b32_e32 v35, 0
	v_mov_b32_e32 v34, 0
	v_mov_b32_e32 v33, 0
	v_mov_b32_e32 v32, 0
	s_and_saveexec_b64 s[38:39], vcc
	s_cbranch_execz .LBB0_1336
	v_cmp_gt_i32_e32 vcc, s68, v43
	v_mov_b32_e32 v32, 0
	v_mov_b32_e32 v33, 0
	v_mov_b32_e32 v34, 0
	v_mov_b32_e32 v35, 0
	s_and_saveexec_b64 s[40:41], vcc
	s_cbranch_execz .LBB0_1329
	v_mad_i64_i32 v[2:3], s[78:79], v0, s68, 0
	v_lshl_add_u64 v[2:3], v[2:3], 2, s[4:5]
	v_lshl_add_u64 v[2:3], s[36:37], 2, v[2:3]
	v_lshlrev_b32_e32 v0, 2, v41
	v_lshl_add_u64 v[2:3], v[2:3], 0, v[0:1]
	global_load_dwordx4 v[32:35], v[2:3], off

.LBB0_1338:
	s_abs_i32 s36, s42
	s_waitcnt vmcnt(0)
	v_cvt_f32_u32_e32 v0, s36
	s_sub_i32 s39, 0, s36
	s_abs_i32 s38, s45
	s_xor_b32 s37, s45, s42
	v_rcp_iflag_f32_e32 v0, v0
	s_ashr_i32 s37, s37, 31
	v_mov_b32_e32 v2, v202
	v_mul_f32_e32 v0, 0x4f7ffffe, v0
	v_cvt_u32_f32_e32 v0, v0
	v_ashrrev_i32_e32 v3, 4, v2
	v_mov_b32_e32 v42, 1.0
	v_readfirstlane_b32 s40, v0
	s_mul_i32 s39, s39, s40
	s_mul_hi_u32 s39, s40, s39
	s_add_i32 s40, s40, s39
	s_mul_hi_u32 s39, s38, s40
	s_mul_i32 s40, s39, s36
	s_sub_i32 s38, s38, s40
	s_add_i32 s41, s39, 1
	s_sub_i32 s40, s38, s36
	s_cmp_ge_u32 s38, s36
	s_cselect_b32 s39, s41, s39
	s_cselect_b32 s38, s40, s38
	s_add_i32 s40, s39, 1
	s_cmp_ge_u32 s38, s36
	s_cselect_b32 s36, s40, s39
	s_xor_b32 s36, s36, s37
	s_sub_i32 s37, s36, s37
	s_mul_i32 s36, s37, s42
	s_sub_i32 s36, s45, s36
	v_lshlrev_b32_e32 v0, 2, v2
	v_lshl_add_u32 v56, s37, 6, v3
	v_mov_b32_e32 v2, v1
	v_mov_b32_e32 v3, v1
	s_lshl_b32 s36, s36, 6
	v_and_b32_e32 v41, 60, v0
	v_mov_b32_e32 v0, v1
	s_waitcnt lgkmcnt(0)
	v_mov_b64_e32 v[10:11], v[2:3]
	v_or_b32_e32 v43, s36, v41
	s_ashr_i32 s37, s36, 31
	v_cmp_gt_i32_e32 vcc, s64, v56
	v_mov_b64_e32 v[8:9], v[0:1]
	s_and_saveexec_b64 s[38:39], vcc
	s_cbranch_execz .LBB0_1348
	v_mov_b32_e32 v2, v1
	v_mov_b32_e32 v3, v1
	v_mov_b32_e32 v0, v1
	v_mov_b64_e32 v[10:11], v[2:3]
	v_cmp_gt_i32_e32 vcc, s68, v43
	v_mov_b64_e32 v[8:9], v[0:1]
	s_and_saveexec_b64 s[40:41], vcc
	s_cbranch_execz .LBB0_1341
	v_mad_i64_i32 v[2:3], s[78:79], v56, s68, 0
	v_lshl_add_u64 v[2:3], v[2:3], 2, s[4:5]
	v_lshl_add_u64 v[2:3], s[36:37], 2, v[2:3]
	v_lshlrev_b32_e32 v0, 2, v41
	v_lshl_add_u64 v[2:3], v[2:3], 0, v[0:1]
	global_load_dwordx4 v[8:11], v[2:3], off
	s_cmp_lt_i32 s64, 64
	s_cbranch_scc1 .Lc2_skip19
	s_and_b32 s100, s68, 63
	s_cmp_lg_u32 s100, 0
	s_cbranch_scc1 .Lc2_skip19
	s_lshl_b32 s100, s68, 7
	v_add_co_u32_e32 v70, vcc, s100, v2
	s_nop 1
	v_addc_co_u32_e32 v71, vcc, 0, v3, vcc
	s_cmp_lg_u32 s70, 0
	s_cbranch_scc1 .Lc2_pf19
	s_mov_b32 s101, 1
	global_load_dwordx4 v[24:27], v[70:71], off
	s_cmp_lg_u64 s[30:31], 0
	s_cbranch_scc0 .Lc2_skip19
	v_add_u32_e32 v66, 32, v56
	v_mov_b32_e32 v67, 0
	v_lshl_add_u64 v[68:69], v[66:67], 2, s[8:9]
	global_load_dword v67, v[68:69], off
	s_branch .Lc2_skip19

.LBB0_1348:
	s_or_b64 exec, exec, s[38:39]
	s_waitcnt vmcnt(0)
	s_cmp_eq_u32 s101, 1
	s_mov_b32 s101, 0
	s_cbranch_scc0 .Lc2_slow19
	v_mov_b32_e32 v54, 1.0
	v_cndmask_b32_e64 v54, v54, v67, s[30:31]
	s_branch .Lc2_end19
.Lc2_slow19:
	v_add_u32_e32 v0, 32, v56
	v_cmp_gt_i32_e32 vcc, s64, v0
	v_mov_b32_e32 v54, 1.0
	v_mov_b32_e32 v27, 0
	v_mov_b32_e32 v26, 0
	v_mov_b32_e32 v25, 0
	v_mov_b32_e32 v24, 0
	s_and_saveexec_b64 s[38:39], vcc
	s_cbranch_execz .LBB0_1358
	v_cmp_gt_i32_e32 vcc, s68, v43
	v_mov_b32_e32 v24, 0
	v_mov_b32_e32 v25, 0
	v_mov_b32_e32 v26, 0
	v_mov_b32_e32 v27, 0
	s_and_saveexec_b64 s[40:41], vcc
	s_cbranch_execz .LBB0_1351
	v_mad_i64_i32 v[2:3], s[78:79], v0, s68, 0
	v_lshl_add_u64 v[2:3], v[2:3], 2, s[4:5]
	v_lshl_add_u64 v[2:3], s[36:37], 2, v[2:3]
	v_lshlrev_b32_e32 v0, 2, v41
	v_lshl_add_u64 v[2:3], v[2:3], 0, v[0:1]
	global_load_dwordx4 v[24:27], v[2:3], off

.LBB0_1358:
	s_or_b64 exec, exec, s[38:39]
.Lc2_end19:
	s_and_b64 vcc, exec, s[34:35]
	s_cbranch_vccz .LBB0_1217
.LBB0_1359:
	s_abs_i32 s77, s42
	s_waitcnt vmcnt(0)
	v_cvt_f32_u32_e32 v0, s77
	s_lshl_b32 s34, s44, 6
	s_lshl_b32 s35, s43, 6
	s_sub_i32 s36, 0, s77
	v_rcp_iflag_f32_e32 v0, v0
	s_sub_i32 s82, s34, s35
	s_lshl_b32 s79, s42, 6
	s_ashr_i32 s78, s42, 31
	v_mul_f32_e32 v0, 0x4f7ffffe, v0
	v_cvt_u32_f32_e32 v0, v0
	s_sub_i32 s84, 0, s79
	v_readfirstlane_b32 s34, v0
	s_mul_i32 s36, s36, s34
	s_mul_hi_u32 s35, s34, s36
	s_add_i32 s83, s34, s35

.LBB0_1373:
	s_or_b64 exec, exec, s[34:35]
	s_add_i32 s85, s76, s94
	s_waitcnt lgkmcnt(0)
	s_barrier
	s_cmp_ge_i32 s85, s72
	s_cselect_b64 s[34:35], -1, 0
	s_and_b64 vcc, exec, s[34:35]
	s_cbranch_vccnz .LBB0_1401
	s_abs_i32 s37, s85
	s_mul_hi_u32 s38, s37, s83
	s_mul_i32 s39, s38, s77
	s_ashr_i32 s36, s85, 31
	s_sub_i32 s37, s37, s39
	s_xor_b32 s36, s36, s78
	s_add_i32 s39, s38, 1
	s_sub_i32 s40, s37, s77
	s_cmp_ge_u32 s37, s77
	s_cselect_b32 s38, s39, s38
	s_cselect_b32 s37, s40, s37
	s_add_i32 s39, s38, 1
	s_cmp_ge_u32 s37, s77
	v_mov_b32_e32 v0, v202
	s_cselect_b32 s37, s39, s38
	s_xor_b32 s37, s37, s36
	s_sub_i32 s37, s37, s36
	v_ashrrev_i32_e32 v2, 4, v0
	v_lshlrev_b32_e32 v0, 2, v0
	s_mul_i32 s36, s84, s37
	v_and_b32_e32 v41, 60, v0
	v_lshl_add_u32 v56, s37, 6, v2
	s_mul_i32 s37, s79, s37
	s_add_i32 s38, s29, s82
	v_subrev_u32_e32 v0, s37, v41
	v_mov_b32_e32 v2, v1
	v_mov_b32_e32 v3, v1
	s_add_i32 s36, s38, s36
	v_add_u32_e32 v43, s38, v0
	v_mov_b32_e32 v0, v1
	v_mov_b64_e32 v[22:23], v[2:3]
	s_ashr_i32 s37, s36, 31
	v_cmp_gt_i32_e32 vcc, s64, v56
	v_mov_b32_e32 v46, 1.0
	v_mov_b64_e32 v[20:21], v[0:1]
	s_and_saveexec_b64 s[38:39], vcc
	s_cbranch_execz .LBB0_1387
	v_mov_b32_e32 v2, v1
	v_mov_b32_e32 v3, v1
	v_mov_b32_e32 v0, v1
	v_mov_b64_e32 v[22:23], v[2:3]
	v_cmp_gt_i32_e32 vcc, s68, v43
	v_mov_b64_e32 v[20:21], v[0:1]
	s_and_saveexec_b64 s[40:41], vcc
	s_cbranch_execz .LBB0_1377
	v_mad_i64_i32 v[2:3], s[42:43], v56, s68, 0
	v_lshl_add_u64 v[2:3], v[2:3], 2, s[4:5]
	v_lshl_add_u64 v[2:3], s[36:37], 2, v[2:3]
	v_lshlrev_b32_e32 v0, 2, v41
	v_lshl_add_u64 v[2:3], v[2:3], 0, v[0:1]
	global_load_dwordx4 v[20:23], v[2:3], off
	s_cmp_lt_i32 s64, 64
	s_cbranch_scc1 .Lc2_skip20
	s_and_b32 s100, s68, 63
	s_cmp_lg_u32 s100, 0
	s_cbranch_scc1 .Lc2_skip20
	s_lshl_b32 s100, s68, 7
	v_add_co_u32_e32 v70, vcc, s100, v2
	s_nop 1
	v_addc_co_u32_e32 v71, vcc, 0, v3, vcc
	s_cmp_lg_u32 s70, 0
	s_cbranch_scc1 .Lc2_pf20
	s_mov_b32 s101, 1
	global_load_dwordx4 v[36:39], v[70:71], off
	s_cmp_lg_u64 s[30:31], 0
	s_cbranch_scc0 .Lc2_skip20
	v_add_u32_e32 v66, 32, v56
	v_mov_b32_e32 v67, 0
	v_lshl_add_u64 v[68:69], v[66:67], 2, s[8:9]
	global_load_dword v67, v[68:69], off
	s_branch .Lc2_skip20

.Lc2_slow20:
	v_add_u32_e32 v0, 32, v56
	v_cmp_gt_i32_e32 vcc, s64, v0
	v_mov_b32_e32 v52, 1.0
	v_mov_b32_e32 v39, 0
	v_mov_b32_e32 v38, 0
	v_mov_b32_e32 v37, 0
	v_mov_b32_e32 v36, 0
	s_and_saveexec_b64 s[38:39], vcc
	s_cbranch_execz .LBB0_1400
	v_cmp_gt_i32_e32 vcc, s68, v43
	v_mov_b32_e32 v36, 0
	v_mov_b32_e32 v37, 0
	v_mov_b32_e32 v38, 0
	v_mov_b32_e32 v39, 0
	s_and_saveexec_b64 s[40:41], vcc
	s_cbranch_execz .LBB0_1390
	v_mad_i64_i32 v[2:3], s[42:43], v0, s68, 0
	v_lshl_add_u64 v[2:3], v[2:3], 2, s[4:5]
	v_lshl_add_u64 v[2:3], s[36:37], 2, v[2:3]
	v_lshlrev_b32_e32 v0, 2, v41
	v_lshl_add_u64 v[2:3], v[2:3], 0, v[0:1]
	global_load_dwordx4 v[36:39], v[2:3], off

.Lc2_end20:
.LBB0_1401:
	s_add_i32 s36, s28, s76
	s_cmp_ge_i32 s36, s72
	s_cbranch_scc1 .LBB0_1443
	s_ashr_i32 s37, s36, 31
	s_abs_i32 s36, s36
	s_mul_hi_u32 s38, s36, s83
	s_mul_i32 s39, s38, s77
	s_sub_i32 s36, s36, s39
	s_xor_b32 s37, s37, s78
	s_add_i32 s39, s38, 1
	s_sub_i32 s40, s36, s77
	s_waitcnt vmcnt(0)
	v_mov_b32_e32 v0, v202
	s_cmp_ge_u32 s36, s77
	s_cselect_b32 s38, s39, s38
	v_ashrrev_i32_e32 v2, 4, v0
	v_lshlrev_b32_e32 v3, 4, v0
	s_cselect_b32 s36, s40, s36
	s_add_i32 s39, s38, 1
	v_and_b32_e32 v3, 0xf0, v3
	v_mul_lo_u32 v2, v2, s3
	s_cmp_ge_u32 s36, s77
	v_add3_u32 v41, 0, v3, v2
	v_pk_mul_f32 v[2:3], v[44:45], v[16:17] op_sel_hi:[0,1]
	s_cselect_b32 s36, s39, s38
	ds_write2_b32 v41, v2, v3 offset1:1
	v_pk_mul_f32 v[2:3], v[44:45], v[18:19] op_sel_hi:[0,1]
	s_xor_b32 s36, s36, s37
	ds_write2_b32 v41, v2, v3 offset0:2 offset1:3
	v_add_u32_e32 v43, 0x2080, v41
	v_pk_mul_f32 v[2:3], v[50:51], v[32:33] op_sel_hi:[0,1]
	s_sub_i32 s38, s36, s37
	ds_write2_b32 v43, v2, v3 offset1:1
	v_add_u32_e32 v41, 0x2088, v41
	v_pk_mul_f32 v[2:3], v[50:51], v[34:35] op_sel_hi:[0,1]
	ds_write2_b32 v41, v2, v3 offset1:1
	v_ashrrev_i32_e32 v2, 3, v0
	s_mul_i32 s36, s79, s38
	s_waitcnt lgkmcnt(0)
	s_barrier
	v_subrev_u32_e32 v3, s36, v2
	s_add_i32 s36, s80, s82
	v_add_u32_e32 v41, s36, v3
	v_cmp_gt_i32_e32 vcc, s68, v41
	s_and_saveexec_b64 s[36:37], vcc
	s_cbranch_execz .LBB0_1415
	v_lshlrev_b32_e32 v0, 3, v0
	s_lshl_b32 s38, s38, 6
	v_and_b32_e32 v0, 56, v0
	v_or_b32_e32 v3, s38, v0
	v_cmp_gt_i32_e32 vcc, s65, v3
	s_and_b64 exec, exec, vcc
	s_cbranch_execz .LBB0_1415
	v_lshlrev_b32_e32 v45, 2, v2
	v_mul_u32_u24_e32 v2, 0x104, v0
	v_add3_u32 v43, 0, v45, v2
	ds_read2_b32 v[2:3], v43 offset1:65
	ds_read2_b32 v[56:57], v43 offset0:130 offset1:195
	v_add_u32_e32 v43, 0x400, v43
	ds_read2_b32 v[58:59], v43 offset0:4 offset1:69
	ds_read2_b32 v[60:61], v43 offset0:134 offset1:199
	s_mov_b64 s[44:45], -1
	s_mov_b64 s[40:41], 0
	s_cmp_lt_i32 s69, 2
	s_mov_b64 s[42:43], 0
	s_cbranch_scc1 .LBB0_1410
	s_cmp_eq_u32 s69, 2
	s_mov_b64 s[42:43], -1
	s_cbranch_scc0 .LBB0_1407
	v_and_b32_e32 v43, 0x80, v45
	v_lshrrev_b32_e32 v45, 1, v41
	v_and_b32_e32 v45, 0x60, v45
	v_and_b32_e32 v47, 0xffffff1f, v41
	v_or3_b32 v43, v47, v43, v45
	s_mov_b64 s[42:43], 0

.LBB0_1415:
	s_or_b64 exec, exec, s[36:37]
	s_waitcnt lgkmcnt(0)
	s_barrier
	s_mul_i32 s36, s28, 5
	s_add_i32 s36, s36, s76
	s_cmp_ge_i32 s36, s72
	s_cbranch_scc1 .LBB0_1443
	s_ashr_i32 s37, s36, 31
	s_abs_i32 s36, s36
	s_mul_hi_u32 s38, s36, s83
	s_mul_i32 s39, s38, s77
	s_sub_i32 s36, s36, s39
	s_xor_b32 s37, s37, s78
	s_add_i32 s39, s38, 1
	s_sub_i32 s40, s36, s77
	s_cmp_ge_u32 s36, s77
	s_cselect_b32 s38, s39, s38
	s_cselect_b32 s36, s40, s36
	s_add_i32 s39, s38, 1
	s_cmp_ge_u32 s36, s77
	v_mov_b32_e32 v0, v202
	s_cselect_b32 s36, s39, s38
	s_xor_b32 s36, s36, s37
	s_sub_i32 s37, s36, s37
	v_ashrrev_i32_e32 v2, 4, v0
	v_lshlrev_b32_e32 v0, 2, v0
	s_mul_i32 s36, s84, s37
	s_mul_i32 s38, s28, 0x140
	v_and_b32_e32 v41, 60, v0
	v_lshl_add_u32 v56, s37, 6, v2
	s_mul_i32 s37, s79, s37
	s_add_i32 s38, s38, s82
	v_subrev_u32_e32 v0, s37, v41
	v_mov_b32_e32 v2, v1
	v_mov_b32_e32 v3, v1
	s_add_i32 s36, s38, s36
	v_add_u32_e32 v43, s38, v0
	v_mov_b32_e32 v0, v1
	v_mov_b64_e32 v[18:19], v[2:3]
	s_ashr_i32 s37, s36, 31
	v_cmp_gt_i32_e32 vcc, s64, v56
	v_mov_b32_e32 v44, 1.0
	v_mov_b64_e32 v[16:17], v[0:1]
	s_and_saveexec_b64 s[38:39], vcc
	s_cbranch_execz .LBB0_1429
	v_mov_b32_e32 v2, v1
	v_mov_b32_e32 v3, v1
	v_mov_b32_e32 v0, v1
	v_mov_b64_e32 v[18:19], v[2:3]
	v_cmp_gt_i32_e32 vcc, s68, v43
	v_mov_b64_e32 v[16:17], v[0:1]
	s_and_saveexec_b64 s[40:41], vcc
	s_cbranch_execz .LBB0_1419
	v_mad_i64_i32 v[2:3], s[42:43], v56, s68, 0
	v_lshl_add_u64 v[2:3], v[2:3], 2, s[4:5]
	v_lshl_add_u64 v[2:3], s[36:37], 2, v[2:3]
	v_lshlrev_b32_e32 v0, 2, v41
	v_lshl_add_u64 v[2:3], v[2:3], 0, v[0:1]
	global_load_dwordx4 v[16:19], v[2:3], off
	s_cmp_lt_i32 s64, 64
	s_cbranch_scc1 .Lc2_skip21
	s_and_b32 s100, s68, 63
	s_cmp_lg_u32 s100, 0
	s_cbranch_scc1 .Lc2_skip21
	s_lshl_b32 s100, s68, 7
	v_add_co_u32_e32 v70, vcc, s100, v2
	s_nop 1
	v_addc_co_u32_e32 v71, vcc, 0, v3, vcc
	s_cmp_lg_u32 s70, 0
	s_cbranch_scc1 .Lc2_pf21
	s_mov_b32 s101, 1
	global_load_dwordx4 v[32:35], v[70:71], off
	s_cmp_lg_u64 s[30:31], 0
	s_cbranch_scc0 .Lc2_skip21
	v_add_u32_e32 v66, 32, v56
	v_mov_b32_e32 v67, 0
	v_lshl_add_u64 v[68:69], v[66:67], 2, s[8:9]
	global_load_dword v67, v[68:69], off
	s_branch .Lc2_skip21

.Lc2_slow21:
	v_add_u32_e32 v0, 32, v56
	v_cmp_gt_i32_e32 vcc, s64, v0
	v_mov_b32_e32 v50, 1.0
	v_mov_b32_e32 v35, 0
	v_mov_b32_e32 v34, 0
	v_mov_b32_e32 v33, 0
	v_mov_b32_e32 v32, 0
	s_and_saveexec_b64 s[38:39], vcc
	s_cbranch_execz .LBB0_1442
	v_cmp_gt_i32_e32 vcc, s68, v43
	v_mov_b32_e32 v32, 0
	v_mov_b32_e32 v33, 0
	v_mov_b32_e32 v34, 0
	v_mov_b32_e32 v35, 0
	s_and_saveexec_b64 s[40:41], vcc
	s_cbranch_execz .LBB0_1432
	v_mad_i64_i32 v[2:3], s[42:43], v0, s68, 0
	v_lshl_add_u64 v[2:3], v[2:3], 2, s[4:5]
	v_lshl_add_u64 v[2:3], s[36:37], 2, v[2:3]
	v_lshlrev_b32_e32 v0, 2, v41
	v_lshl_add_u64 v[2:3], v[2:3], 0, v[0:1]
	global_load_dwordx4 v[32:35], v[2:3], off

.Lc2_end21:
.LBB0_1443:
	s_add_i32 s36, s95, s76
	s_cmp_ge_i32 s36, s72
	s_cbranch_scc1 .LBB0_1485
	s_ashr_i32 s37, s36, 31
	s_abs_i32 s36, s36
	s_mul_hi_u32 s38, s36, s83
	s_mul_i32 s39, s38, s77
	s_sub_i32 s36, s36, s39
	s_waitcnt vmcnt(0)
	v_mov_b32_e32 v0, v202
	s_xor_b32 s37, s37, s78
	s_add_i32 s39, s38, 1
	s_sub_i32 s40, s36, s77
	s_cmp_ge_u32 s36, s77
	v_ashrrev_i32_e32 v2, 4, v0
	v_lshlrev_b32_e32 v3, 4, v0
	s_cselect_b32 s38, s39, s38
	v_and_b32_e32 v3, 0xf0, v3
	v_mul_lo_u32 v2, v2, s3
	s_cselect_b32 s36, s40, s36
	s_add_i32 s39, s38, 1
	v_add3_u32 v41, 0, v3, v2
	s_cmp_ge_u32 s36, s77
	v_pk_mul_f32 v[2:3], v[40:41], v[12:13] op_sel_hi:[0,1]
	s_cselect_b32 s36, s39, s38
	ds_write2_b32 v41, v2, v3 offset1:1
	v_pk_mul_f32 v[2:3], v[40:41], v[14:15] op_sel_hi:[0,1]
	s_xor_b32 s36, s36, s37
	ds_write2_b32 v41, v2, v3 offset0:2 offset1:3
	v_add_u32_e32 v43, 0x2080, v41
	v_pk_mul_f32 v[2:3], v[48:49], v[28:29] op_sel_hi:[0,1]
	s_sub_i32 s38, s36, s37
	ds_write2_b32 v43, v2, v3 offset1:1
	v_add_u32_e32 v41, 0x2088, v41
	v_pk_mul_f32 v[2:3], v[48:49], v[30:31] op_sel_hi:[0,1]
	ds_write2_b32 v41, v2, v3 offset1:1
	v_ashrrev_i32_e32 v2, 3, v0
	s_mul_i32 s36, s79, s38
	s_waitcnt lgkmcnt(0)
	s_barrier
	v_subrev_u32_e32 v3, s36, v2
	s_add_i32 s36, s81, s82
	v_add_u32_e32 v41, s36, v3
	v_cmp_gt_i32_e32 vcc, s68, v41
	s_and_saveexec_b64 s[36:37], vcc
	s_cbranch_execz .LBB0_1457
	v_lshlrev_b32_e32 v0, 3, v0
	s_lshl_b32 s38, s38, 6
	v_and_b32_e32 v0, 56, v0
	v_or_b32_e32 v3, s38, v0
	v_cmp_gt_i32_e32 vcc, s65, v3
	s_and_b64 exec, exec, vcc
	s_cbranch_execz .LBB0_1457
	v_lshlrev_b32_e32 v45, 2, v2
	v_mul_u32_u24_e32 v2, 0x104, v0
	v_add3_u32 v43, 0, v45, v2
	ds_read2_b32 v[2:3], v43 offset1:65
	ds_read2_b32 v[56:57], v43 offset0:130 offset1:195
	v_add_u32_e32 v43, 0x400, v43
	ds_read2_b32 v[58:59], v43 offset0:4 offset1:69
	ds_read2_b32 v[60:61], v43 offset0:134 offset1:199
	s_mov_b64 s[44:45], -1
	s_mov_b64 s[40:41], 0
	s_cmp_lt_i32 s69, 2
	s_mov_b64 s[42:43], 0
	s_cbranch_scc1 .LBB0_1452
	s_cmp_eq_u32 s69, 2
	s_mov_b64 s[42:43], -1
	s_cbranch_scc0 .LBB0_1449
	v_and_b32_e32 v43, 0x80, v45
	v_lshrrev_b32_e32 v45, 1, v41
	v_and_b32_e32 v45, 0x60, v45
	v_and_b32_e32 v47, 0xffffff1f, v41
	v_or3_b32 v43, v47, v43, v45
	s_mov_b64 s[42:43], 0

.LBB0_1457:
	s_or_b64 exec, exec, s[36:37]
	s_waitcnt lgkmcnt(0)
	s_barrier
	s_mul_i32 s36, s28, 6
	s_add_i32 s36, s36, s76
	s_cmp_ge_i32 s36, s72
	s_cbranch_scc1 .LBB0_1485
	s_ashr_i32 s37, s36, 31
	s_abs_i32 s36, s36
	s_mul_hi_u32 s38, s36, s83
	s_mul_i32 s39, s38, s77
	s_sub_i32 s36, s36, s39
	s_xor_b32 s37, s37, s78
	s_add_i32 s39, s38, 1
	s_sub_i32 s40, s36, s77
	s_cmp_ge_u32 s36, s77
	s_cselect_b32 s38, s39, s38
	s_cselect_b32 s36, s40, s36
	s_add_i32 s39, s38, 1
	s_cmp_ge_u32 s36, s77
	v_mov_b32_e32 v0, v202
	s_cselect_b32 s36, s39, s38
	s_xor_b32 s36, s36, s37
	s_sub_i32 s37, s36, s37
	v_ashrrev_i32_e32 v2, 4, v0
	v_lshlrev_b32_e32 v0, 2, v0
	s_mul_i32 s36, s84, s37
	s_mul_i32 s38, s28, 0x180
	v_and_b32_e32 v41, 60, v0
	v_lshl_add_u32 v56, s37, 6, v2
	s_mul_i32 s37, s79, s37
	s_add_i32 s38, s38, s82
	v_subrev_u32_e32 v0, s37, v41
	v_mov_b32_e32 v2, v1
	v_mov_b32_e32 v3, v1
	s_add_i32 s36, s38, s36
	v_add_u32_e32 v43, s38, v0
	v_mov_b32_e32 v0, v1
	v_mov_b64_e32 v[14:15], v[2:3]
	s_ashr_i32 s37, s36, 31
	v_cmp_gt_i32_e32 vcc, s64, v56
	v_mov_b32_e32 v40, 1.0
	v_mov_b64_e32 v[12:13], v[0:1]
	s_and_saveexec_b64 s[38:39], vcc
	s_cbranch_execz .LBB0_1471
	v_mov_b32_e32 v2, v1
	v_mov_b32_e32 v3, v1
	v_mov_b32_e32 v0, v1
	v_mov_b64_e32 v[14:15], v[2:3]
	v_cmp_gt_i32_e32 vcc, s68, v43
	v_mov_b64_e32 v[12:13], v[0:1]
	s_and_saveexec_b64 s[40:41], vcc
	s_cbranch_execz .LBB0_1461
	v_mad_i64_i32 v[2:3], s[42:43], v56, s68, 0
	v_lshl_add_u64 v[2:3], v[2:3], 2, s[4:5]
	v_lshl_add_u64 v[2:3], s[36:37], 2, v[2:3]
	v_lshlrev_b32_e32 v0, 2, v41
	v_lshl_add_u64 v[2:3], v[2:3], 0, v[0:1]
	global_load_dwordx4 v[12:15], v[2:3], off
	s_cmp_lt_i32 s64, 64
	s_cbranch_scc1 .Lc2_skip22
	s_and_b32 s100, s68, 63
	s_cmp_lg_u32 s100, 0
	s_cbranch_scc1 .Lc2_skip22
	s_lshl_b32 s100, s68, 7
	v_add_co_u32_e32 v70, vcc, s100, v2
	s_nop 1
	v_addc_co_u32_e32 v71, vcc, 0, v3, vcc
	s_cmp_lg_u32 s70, 0
	s_cbranch_scc1 .Lc2_pf22
	s_mov_b32 s101, 1
	global_load_dwordx4 v[28:31], v[70:71], off
	s_cmp_lg_u64 s[30:31], 0
	s_cbranch_scc0 .Lc2_skip22
	v_add_u32_e32 v66, 32, v56
	v_mov_b32_e32 v67, 0
	v_lshl_add_u64 v[68:69], v[66:67], 2, s[8:9]
	global_load_dword v67, v[68:69], off
	s_branch .Lc2_skip22

.Lc2_slow22:
	v_add_u32_e32 v0, 32, v56
	v_cmp_gt_i32_e32 vcc, s64, v0
	v_mov_b32_e32 v48, 1.0
	v_mov_b32_e32 v31, 0
	v_mov_b32_e32 v30, 0
	v_mov_b32_e32 v29, 0
	v_mov_b32_e32 v28, 0
	s_and_saveexec_b64 s[38:39], vcc
	s_cbranch_execz .LBB0_1484
	v_cmp_gt_i32_e32 vcc, s68, v43
	v_mov_b32_e32 v28, 0
	v_mov_b32_e32 v29, 0
	v_mov_b32_e32 v30, 0
	v_mov_b32_e32 v31, 0
	s_and_saveexec_b64 s[40:41], vcc
	s_cbranch_execz .LBB0_1474
	v_mad_i64_i32 v[2:3], s[42:43], v0, s68, 0
	v_lshl_add_u64 v[2:3], v[2:3], 2, s[4:5]
	v_lshl_add_u64 v[2:3], s[36:37], 2, v[2:3]
	v_lshlrev_b32_e32 v0, 2, v41
	v_lshl_add_u64 v[2:3], v[2:3], 0, v[0:1]
	global_load_dwordx4 v[28:31], v[2:3], off

.Lc2_end22:
.LBB0_1485:
	s_add_i32 s36, s33, s76
	s_cmp_ge_i32 s36, s72
	s_cbranch_scc1 .LBB0_1527
	s_ashr_i32 s37, s36, 31
	s_abs_i32 s36, s36
	s_mul_hi_u32 s38, s36, s83
	s_mul_i32 s39, s38, s77
	s_sub_i32 s36, s36, s39
	s_xor_b32 s37, s37, s78
	s_add_i32 s39, s38, 1
	s_sub_i32 s40, s36, s77
	s_waitcnt vmcnt(0)
	v_mov_b32_e32 v0, v202
	s_cmp_ge_u32 s36, s77
	s_cselect_b32 s38, s39, s38
	v_ashrrev_i32_e32 v2, 4, v0
	v_lshlrev_b32_e32 v3, 4, v0
	s_cselect_b32 s36, s40, s36
	s_add_i32 s39, s38, 1
	v_and_b32_e32 v3, 0xf0, v3
	v_mul_lo_u32 v2, v2, s3
	s_cmp_ge_u32 s36, s77
	v_add3_u32 v41, 0, v3, v2
	s_waitcnt lgkmcnt(4)
	v_pk_mul_f32 v[2:3], v[8:9], v[42:43] op_sel_hi:[1,0]
	s_cselect_b32 s36, s39, s38
	ds_write2_b32 v41, v2, v3 offset1:1
	v_pk_mul_f32 v[2:3], v[10:11], v[42:43] op_sel_hi:[1,0]
	s_xor_b32 s36, s36, s37
	ds_write2_b32 v41, v2, v3 offset0:2 offset1:3
	v_add_u32_e32 v43, 0x2080, v41
	v_pk_mul_f32 v[2:3], v[24:25], v[54:55] op_sel_hi:[1,0]
	s_sub_i32 s38, s36, s37
	ds_write2_b32 v43, v2, v3 offset1:1
	v_add_u32_e32 v41, 0x2088, v41
	v_pk_mul_f32 v[2:3], v[26:27], v[54:55] op_sel_hi:[1,0]
	ds_write2_b32 v41, v2, v3 offset1:1
	v_ashrrev_i32_e32 v2, 3, v0
	s_mul_i32 s36, s79, s38
	v_subrev_u32_e32 v3, s36, v2
	s_mul_i32 s36, s28, 0xc0
	s_waitcnt lgkmcnt(0)
	s_barrier
	s_add_i32 s36, s36, s82
	v_add_u32_e32 v41, s36, v3
	v_cmp_gt_i32_e32 vcc, s68, v41
	s_and_saveexec_b64 s[36:37], vcc
	s_cbranch_execz .LBB0_1499
	v_lshlrev_b32_e32 v0, 3, v0
	s_lshl_b32 s38, s38, 6
	v_and_b32_e32 v0, 56, v0
	v_or_b32_e32 v3, s38, v0
	v_cmp_gt_i32_e32 vcc, s65, v3
	s_and_b64 exec, exec, vcc
	s_cbranch_execz .LBB0_1499
	v_lshlrev_b32_e32 v45, 2, v2
	v_mul_u32_u24_e32 v2, 0x104, v0
	v_add3_u32 v43, 0, v45, v2
	ds_read2_b32 v[2:3], v43 offset1:65
	ds_read2_b32 v[56:57], v43 offset0:130 offset1:195
	v_add_u32_e32 v43, 0x400, v43
	ds_read2_b32 v[58:59], v43 offset0:4 offset1:69
	ds_read2_b32 v[60:61], v43 offset0:134 offset1:199
	s_mov_b64 s[44:45], -1
	s_mov_b64 s[40:41], 0
	s_cmp_lt_i32 s69, 2
	s_mov_b64 s[42:43], 0
	s_cbranch_scc1 .LBB0_1494
	s_cmp_eq_u32 s69, 2
	s_mov_b64 s[42:43], -1
	s_cbranch_scc0 .LBB0_1491
	v_and_b32_e32 v43, 0x80, v45
	v_lshrrev_b32_e32 v45, 1, v41
	v_and_b32_e32 v45, 0x60, v45
	v_and_b32_e32 v47, 0xffffff1f, v41
	v_or3_b32 v43, v47, v43, v45
	s_mov_b64 s[42:43], 0

.LBB0_1499:
	s_or_b64 exec, exec, s[36:37]
	s_waitcnt lgkmcnt(0)
	s_barrier
	s_mul_i32 s36, s28, 7
	s_add_i32 s36, s36, s76
	s_cmp_ge_i32 s36, s72
	s_cbranch_scc1 .LBB0_1527
	s_ashr_i32 s37, s36, 31
	s_abs_i32 s36, s36
	s_mul_hi_u32 s38, s36, s83
	s_mul_i32 s39, s38, s77
	s_sub_i32 s36, s36, s39
	s_xor_b32 s37, s37, s78
	s_add_i32 s39, s38, 1
	s_sub_i32 s40, s36, s77
	s_cmp_ge_u32 s36, s77
	s_cselect_b32 s38, s39, s38
	s_cselect_b32 s36, s40, s36
	s_add_i32 s39, s38, 1
	s_cmp_ge_u32 s36, s77
	v_mov_b32_e32 v0, v202
	s_cselect_b32 s36, s39, s38
	s_xor_b32 s36, s36, s37
	s_sub_i32 s37, s36, s37
	v_ashrrev_i32_e32 v2, 4, v0
	v_lshlrev_b32_e32 v0, 2, v0
	s_mul_i32 s36, s84, s37
	s_mul_i32 s38, s28, 0x1c0
	v_and_b32_e32 v41, 60, v0
	v_lshl_add_u32 v56, s37, 6, v2
	s_mul_i32 s37, s79, s37
	s_add_i32 s38, s38, s82
	v_subrev_u32_e32 v0, s37, v41
	v_mov_b32_e32 v2, v1
	v_mov_b32_e32 v3, v1
	s_add_i32 s36, s38, s36
	v_add_u32_e32 v43, s38, v0
	v_mov_b32_e32 v0, v1
	v_mov_b64_e32 v[10:11], v[2:3]
	s_ashr_i32 s37, s36, 31
	v_cmp_gt_i32_e32 vcc, s64, v56
	v_mov_b32_e32 v42, 1.0
	v_mov_b64_e32 v[8:9], v[0:1]
	s_and_saveexec_b64 s[38:39], vcc
	s_cbranch_execz .LBB0_1513
	v_mov_b32_e32 v2, v1
	v_mov_b32_e32 v3, v1
	v_mov_b32_e32 v0, v1
	v_mov_b64_e32 v[10:11], v[2:3]
	v_cmp_gt_i32_e32 vcc, s68, v43
	v_mov_b64_e32 v[8:9], v[0:1]
	s_and_saveexec_b64 s[40:41], vcc
	s_cbranch_execz .LBB0_1503
	v_mad_i64_i32 v[2:3], s[42:43], v56, s68, 0
	v_lshl_add_u64 v[2:3], v[2:3], 2, s[4:5]
	v_lshl_add_u64 v[2:3], s[36:37], 2, v[2:3]
	v_lshlrev_b32_e32 v0, 2, v41
	v_lshl_add_u64 v[2:3], v[2:3], 0, v[0:1]
	global_load_dwordx4 v[8:11], v[2:3], off
	s_cmp_lt_i32 s64, 64
	s_cbranch_scc1 .Lc2_skip23
	s_and_b32 s100, s68, 63
	s_cmp_lg_u32 s100, 0
	s_cbranch_scc1 .Lc2_skip23
	s_lshl_b32 s100, s68, 7
	v_add_co_u32_e32 v70, vcc, s100, v2
	s_nop 1
	v_addc_co_u32_e32 v71, vcc, 0, v3, vcc
	s_cmp_lg_u32 s70, 0
	s_cbranch_scc1 .Lc2_pf23
	s_mov_b32 s101, 1
	global_load_dwordx4 v[24:27], v[70:71], off
	s_cmp_lg_u64 s[30:31], 0
	s_cbranch_scc0 .Lc2_skip23
	v_add_u32_e32 v66, 32, v56
	v_mov_b32_e32 v67, 0
	v_lshl_add_u64 v[68:69], v[66:67], 2, s[8:9]
	global_load_dword v67, v[68:69], off
	s_branch .Lc2_skip23

.Lc2_slow23:
	v_add_u32_e32 v0, 32, v56
	v_cmp_gt_i32_e32 vcc, s64, v0
	v_mov_b32_e32 v54, 1.0
	v_mov_b32_e32 v27, 0
	v_mov_b32_e32 v26, 0
	v_mov_b32_e32 v25, 0
	v_mov_b32_e32 v24, 0
	s_and_saveexec_b64 s[38:39], vcc
	s_cbranch_execz .LBB0_1526
	v_cmp_gt_i32_e32 vcc, s68, v43
	v_mov_b32_e32 v24, 0
	v_mov_b32_e32 v25, 0
	v_mov_b32_e32 v26, 0
	v_mov_b32_e32 v27, 0
	s_and_saveexec_b64 s[40:41], vcc
	s_cbranch_execz .LBB0_1516
	v_mad_i64_i32 v[2:3], s[42:43], v0, s68, 0
	v_lshl_add_u64 v[2:3], v[2:3], 2, s[4:5]
	v_lshl_add_u64 v[2:3], s[36:37], 2, v[2:3]
	v_lshlrev_b32_e32 v0, 2, v41
	v_lshl_add_u64 v[2:3], v[2:3], 0, v[0:1]
	global_load_dwordx4 v[24:27], v[2:3], off

.Lc2_end23:
.LBB0_1527:
	s_andn2_b64 vcc, exec, s[34:35]
	s_add_i32 s82, s82, s29
	s_cbranch_vccz .LBB0_1216
	s_mov_b32 s76, s85
	s_branch .LBB0_1360

.LBB0_1709:
	s_or_b64 exec, exec, s[38:39]
.Lc2_end27:
	s_and_b64 vcc, exec, s[34:35]
	s_cbranch_vccz .LBB0_1568
.LBB0_1710:
	s_abs_i32 s77, s42
	s_waitcnt vmcnt(0)
	v_cvt_f32_u32_e32 v0, s77
	s_lshl_b32 s34, s44, 6
	s_lshl_b32 s35, s43, 6
	s_sub_i32 s36, 0, s77
	v_rcp_iflag_f32_e32 v0, v0
	s_sub_i32 s82, s34, s35
	s_lshl_b32 s79, s42, 6
	s_ashr_i32 s78, s42, 31
	v_mul_f32_e32 v0, 0x4f7ffffe, v0
	v_cvt_u32_f32_e32 v0, v0
	s_sub_i32 s84, 0, s79
	v_readfirstlane_b32 s34, v0
	s_mul_i32 s36, s36, s34
	s_mul_hi_u32 s35, s34, s36
	s_add_i32 s83, s34, s35
